# HGRN2 recurrence rewritten with role-split waves (4 waves elementwise part of chunk c+1, 4 waves scores/output/state of chunk c, one barrier per chunk), 2a split 18:14
# speedup vs baseline: 1.0812x; 1.0412x over previous
.LBB0_268:
	s_add_u32 s48, s98, 0xd900000
	s_addc_u32 s49, s99, 0
	s_add_u32 s76, s98, 0xfb00000
	s_addc_u32 s77, s99, 0
	s_cmp_lt_i32 s4, 3
	s_cselect_b64 s[0:1], -1, 0
	s_cmp_gt_i32 s5, 2
	s_cselect_b64 s[2:3], -1, 0
	s_and_b64 s[0:1], s[0:1], s[2:3]
	s_andn2_b64 vcc, exec, s[0:1]
	s_cbranch_vccnz .LBB0_518
	v_readlane_b32 s2, v250, 3
	s_and_b32 s0, s2, 16
	s_bitcmp1_b32 s2, 4
	s_cselect_b64 s[4:5], -1, 0
	s_ashr_i32 s1, s2, 1
	s_and_b32 s1, s1, -16
	s_and_b32 s2, s2, 15
	v_writelane_b32 v250, s4, 16
	s_or_b32 s1, s1, s2
	v_mov_b32_e32 v1, v0
	v_writelane_b32 v250, s5, 17
	s_lshl_b32 s4, s1, 5
	s_or_b32 s5, s4, 18
	s_cmp_eq_u32 s0, 0
	v_writelane_b32 v250, s1, 18
	s_cselect_b64 s[0:1], -1, 0
	s_and_b64 s[2:3], s[0:1], exec
	s_cselect_b32 s33, s4, s5
	s_ashr_i32 s2, s33, 10
	s_ashr_i32 s3, s2, 31
	s_lshl_b32 s4, s33, 5
	s_lshl_b64 s[2:3], s[2:3], 12
	s_and_b32 s10, s4, 0xfc0
	s_or_b32 s2, s2, s10
	v_ashrrev_i32_e32 v8, 3, v1
	v_lshlrev_b32_e32 v2, 3, v1
	v_ashrrev_i32_e32 v9, 31, v8
	v_and_b32_e32 v7, 56, v2
	v_lshl_add_u64 v[2:3], s[2:3], 0, v[8:9]
	s_movk_i32 s6, 0x2600
	v_mov_b64_e32 v[4:5], s[64:65]
	v_mad_u64_u32 v[4:5], s[4:5], v2, s6, v[4:5]
	v_mov_b32_e32 v6, 0
	v_mad_i32_i24 v5, v3, s6, v5
	v_lshlrev_b32_e32 v46, 1, v7
	v_mov_b32_e32 v47, v6
	v_lshl_add_u64 v[26:27], v[4:5], 0, v[46:47]
	s_and_b32 s8, s33, 1
	s_lshl_b32 s8, s8, 7
	s_mov_b32 s9, 0
	v_lshl_add_u64 v[26:27], v[26:27], 0, s[8:9]
	v_add_co_u32_e32 v2, vcc, 0x1000, v26
	v_add_u32_e32 v7, s10, v8
	s_nop 0
	v_addc_co_u32_e32 v3, vcc, 0, v27, vcc
	global_load_dwordx4 v[2:5], v[2:3], off
	v_cmp_lt_i32_e64 s[6:7], 0, v7
	v_mov_b32_e32 v10, 0
	v_mov_b32_e32 v11, 0
	v_mov_b32_e32 v12, 0
	v_mov_b32_e32 v13, 0
	s_and_saveexec_b64 s[4:5], s[6:7]
	s_cbranch_execz .LBB0_271
	v_add_co_u32_e32 v8, vcc, 0xfffff000, v26
	s_nop 1
	v_addc_co_u32_e32 v9, vcc, -1, v27, vcc
	global_load_dwordx4 v[10:13], v[8:9], off offset:-1536

.LBB0_293:
	s_or_b64 exec, exec, s[4:5]
	v_and_b32_e32 v26, 64, v0
	s_and_b64 s[0:1], s[0:1], exec
	v_cmp_eq_u32_e32 vcc, 0, v26
	v_mov_b32_e32 v26, s69
	v_mov_b32_e32 v27, s67
	v_cndmask_b32_e32 v27, v26, v27, vcc
	v_mov_b32_e32 v26, s68
	v_mov_b32_e32 v28, s66
	s_movk_i32 s0, 0x100
	v_cndmask_b32_e32 v26, v26, v28, vcc
	v_cmp_gt_u32_e64 s[2:3], s0, v0
	v_mov_b32_e32 v28, 0x880
	v_mov_b32_e32 v46, 0x800
	v_lshrrev_b32_e32 v170, 1, v0
	v_and_b32_e32 v1, 63, v0
	v_writelane_b32 v250, s2, 21
	s_cselect_b32 s72, 18, 14
	s_add_u32 s88, s96, 0x2000000
	v_cndmask_b32_e64 v28, v28, v46, s[2:3]
	v_and_b32_e32 v46, 64, v170
	v_or3_b32 v28, v28, v46, v1
	v_lshlrev_b32_e32 v28, 2, v28
	v_lshl_add_u64 v[26:27], v[26:27], 0, v[28:29]
	global_load_dword v26, v[26:27], off
	s_addc_u32 s89, s97, 0
	s_add_i32 s0, 0, 0x24000
	s_lshl_b32 s55, s50, 4
	s_cmpk_gt_u32 s51, 0xff
	s_cselect_b64 s[4:5], -1, 0
	s_cmpk_lt_u32 s51, 0x100
	s_cselect_b64 vcc, -1, 0
	v_writelane_b32 v250, s3, 22
	s_and_b64 s[2:3], vcc, exec
	s_cselect_b32 s3, s45, s47
	s_cselect_b32 s2, s44, s46
	v_and_b32_e32 v110, 48, v0
	v_mov_b32_e32 v111, v29
	v_lshl_add_u32 v27, v0, 2, s0
	v_lshl_add_u64 v[112:113], s[2:3], 0, v[110:111]
	s_movk_i32 s2, 0x340
	v_cmp_gt_u32_e64 s[2:3], s2, v0
	v_bfe_u32 v171, v0, 4, 2
	s_mov_b32 s23, 0x1dc00
	v_writelane_b32 v250, s2, 23
	v_and_b32_e32 v166, 15, v0
	v_lshlrev_b32_e32 v173, 2, v171
	v_writelane_b32 v250, s3, 24
	s_mov_b32 s3, 0xd000
	s_cselect_b32 s2, 0, 0x4000
	s_cselect_b32 s22, s3, 0xf800
	v_or_b32_e32 v54, 16, v166
	v_or_b32_e32 v51, 32, v166
	v_bitop3_b32 v28, s50, v171, 3 bitop3:0x6c
	s_movk_i32 s73, 0xa0
	v_or_b32_e32 v49, 48, v1
	v_lshlrev_b32_e32 v48, 6, v28
	v_lshlrev_b32_e32 v28, 2, v166
	v_mul_u32_u24_e32 v46, 0xa0, v49
	v_lshlrev_b32_e32 v188, 2, v1
	v_and_b32_e32 v72, 4, v173
	v_lshrrev_b32_e32 v111, 3, v0
	v_or_b32_e32 v184, s55, v166
	v_mul_lo_u32 v185, v184, s73
	v_lshlrev_b32_e32 v172, 3, v171
	v_lshlrev_b32_e32 v61, 1, v166
	v_lshl_add_u32 v63, v166, 6, 0
	s_mov_b32 s1, 0
	v_and_or_b32 v176, s55, 48, v166
	v_or_b32_e32 v177, 0x200, v0
	v_or_b32_e32 v178, 0x400, v0
	v_or_b32_e32 v179, 0x600, v0
	v_mul_u32_u24_e32 v167, 0xa0, v166
	v_add_u32_e32 v205, 0x24800, v175
	v_lshrrev_b32_e32 v187, 6, v0
	v_add_u32_e32 v215, v63, v110
	v_mov_b32_e32 v220, 0x90
	v_mov_b32_e32 v138, 0
	s_waitcnt vmcnt(0)
	ds_write_b32 v27, v26
	v_and_b32_e32 v27, 7, v0
	v_lshl_add_u32 v180, v27, 5, s0
	s_mov_b32 s0, 0x8000
	s_cselect_b32 s0, s0, 0xa800
	s_add_i32 s0, s0, 0
	v_add_u32_e32 v181, s0, v110
	s_add_i32 s0, s2, 0
	v_lshl_add_u32 v47, v171, 10, s0
	s_lshl_b32 s0, s50, 8
	s_lshl_b32 s92, s50, 1
	s_add_i32 s0, s0, 0
	s_cmp_lt_u32 s51, 64
	s_cselect_b64 s[8:9], -1, 0
	s_cmpk_gt_u32 s51, 0x7f
	s_cselect_b64 s[10:11], -1, 0
	s_cmpk_gt_u32 s51, 0xbf
	s_cselect_b64 s[12:13], -1, 0
	s_cmpk_gt_u32 s51, 0x13f
	s_cselect_b64 s[14:15], -1, 0
	s_cmpk_gt_u32 s51, 0x17f
	s_cselect_b64 s[16:17], -1, 0
	s_cmpk_gt_u32 s51, 0x1bf
	s_cselect_b64 s[18:19], -1, 0
	s_cmpk_gt_u32 s51, 0x1ff
	v_writelane_b32 v250, s0, 25
	s_cselect_b64 s[20:21], -1, 0
	s_lshr_b32 s0, s51, 7
	s_cmp_eq_u32 s0, 2
	s_cselect_b64 s[2:3], -1, 0
	s_and_b64 s[6:7], s[2:3], exec
	s_cselect_b32 s6, s23, 0x20400
	s_cmp_lg_u32 s0, 1
	s_cselect_b32 s23, s6, 0x4000
	s_cmpk_lt_u32 s51, 0x80
	s_cselect_b64 s[24:25], -1, 0
	s_and_b64 s[6:7], s[24:25], exec
	s_cselect_b32 s6, 0, s23
	v_writelane_b32 v250, s24, 26
	s_or_b64 s[2:3], s[24:25], s[2:3]
	s_mov_b32 s7, 0x14800
	s_and_b64 s[2:3], s[2:3], exec
	s_cselect_b32 s7, s7, 0x12000
	s_bfe_u32 s54, s51, 0x10006
	s_bitcmp1_b32 s51, 6
	s_cselect_b64 s[2:3], -1, 0
	s_add_i32 s22, s22, 0
	v_writelane_b32 v250, s25, 27
	v_mov_b32_e32 v53, s22
	v_cmp_lt_u32_e64 s[22:23], v173, v166
	v_cmp_le_u32_e64 s[24:25], v173, v166
	s_add_i32 s7, s7, 0
	v_cndmask_b32_e64 v56, 0, 1, s[22:23]
	v_cndmask_b32_e64 v57, 0, 1, s[24:25]
	v_cndmask_b32_e32 v56, v57, v56, vcc
	v_and_b32_e32 v56, 1, v56
	v_cmp_eq_u32_e64 s[22:23], 1, v56
	v_or_b32_e32 v56, 17, v173
	v_cmp_lt_u32_e64 s[24:25], v56, v54
	v_cmp_le_u32_e64 s[26:27], v56, v54
	s_add_i32 s6, s6, 0
	v_cndmask_b32_e64 v56, 0, 1, s[24:25]
	v_cndmask_b32_e64 v57, 0, 1, s[26:27]
	v_cndmask_b32_e32 v56, v57, v56, vcc
	v_and_b32_e32 v56, 1, v56
	v_mov_b32_e32 v52, s7
	v_mov_b32_e32 v55, s6
	v_cmp_eq_u32_e64 s[6:7], 1, v56
	v_or_b32_e32 v56, 18, v173
	v_cmp_lt_u32_e64 s[26:27], v56, v54
	v_cmp_le_u32_e64 s[28:29], v56, v54
	v_writelane_b32 v250, s6, 28
	v_cndmask_b32_e64 v56, 0, 1, s[26:27]
	v_cndmask_b32_e64 v57, 0, 1, s[28:29]
	v_cndmask_b32_e32 v56, v57, v56, vcc
	v_and_b32_e32 v56, 1, v56
	v_writelane_b32 v250, s7, 29
	v_cmp_eq_u32_e64 s[6:7], 1, v56
	v_or_b32_e32 v56, 19, v173
	v_cmp_lt_u32_e64 s[28:29], v56, v54
	v_cmp_le_u32_e64 s[30:31], v56, v54
	v_writelane_b32 v250, s6, 30
	v_cndmask_b32_e64 v54, 0, 1, s[28:29]
	v_cndmask_b32_e64 v56, 0, 1, s[30:31]
	v_cndmask_b32_e32 v54, v56, v54, vcc
	v_and_b32_e32 v54, 1, v54
	v_writelane_b32 v250, s7, 31
	v_cmp_eq_u32_e64 s[6:7], 1, v54
	v_or_b32_e32 v54, 33, v173
	v_cmp_lt_u32_e64 s[30:31], v54, v51
	v_cmp_le_u32_e64 s[34:35], v54, v51
	v_writelane_b32 v250, s6, 32
	v_cndmask_b32_e64 v54, 0, 1, s[30:31]
	v_cndmask_b32_e64 v57, 0, 1, s[34:35]
	v_cndmask_b32_e32 v54, v57, v54, vcc
	v_and_b32_e32 v54, 1, v54
	v_writelane_b32 v250, s7, 33
	v_cmp_eq_u32_e64 s[6:7], 1, v54
	v_or_b32_e32 v54, 34, v173
	v_cmp_lt_u32_e64 s[34:35], v54, v51
	v_cmp_le_u32_e64 s[36:37], v54, v51
	v_writelane_b32 v250, s6, 34
	v_cndmask_b32_e64 v54, 0, 1, s[34:35]
	v_cndmask_b32_e64 v57, 0, 1, s[36:37]
	v_cndmask_b32_e32 v54, v57, v54, vcc
	v_and_b32_e32 v54, 1, v54
	v_writelane_b32 v250, s7, 35
	v_cmp_eq_u32_e64 s[6:7], 1, v54
	v_or_b32_e32 v54, 35, v173
	v_cmp_lt_u32_e64 s[36:37], v54, v51
	v_cmp_le_u32_e64 s[38:39], v54, v51
	v_writelane_b32 v250, s6, 36
	v_cndmask_b32_e64 v51, 0, 1, s[36:37]
	v_cndmask_b32_e64 v54, 0, 1, s[38:39]
	v_cndmask_b32_e32 v51, v54, v51, vcc
	v_and_b32_e32 v51, 1, v51
	v_add3_u32 v182, v47, v48, v28
	v_mad_u32_u24 v47, v166, s73, v52
	v_mad_u32_u24 v48, v166, s73, v53
	v_writelane_b32 v250, s7, 37
	v_cmp_eq_u32_e64 s[6:7], 1, v51
	v_mad_u32_u24 v51, v49, s73, v53
	v_mad_u32_u24 v53, v49, s73, v52
	v_cndmask_b32_e64 v52, 0, 1, vcc
	v_writelane_b32 v250, s6, 38
	v_or_b32_e32 v52, v173, v52
	v_mad_u32_u24 v183, v166, s73, v55
	v_writelane_b32 v250, s7, 39
	v_cmp_gt_u32_e64 s[6:7], v166, v52
	v_or_b32_e32 v52, 2, v173
	v_cmp_lt_u32_e64 s[40:41], v52, v166
	v_cmp_le_u32_e64 s[42:43], v52, v166
	v_writelane_b32 v250, s6, 40
	v_cndmask_b32_e64 v52, 0, 1, s[40:41]
	v_cndmask_b32_e64 v54, 0, 1, s[42:43]
	v_cndmask_b32_e32 v52, v54, v52, vcc
	v_and_b32_e32 v52, 1, v52
	v_writelane_b32 v250, s7, 41
	v_cmp_eq_u32_e64 s[6:7], 1, v52
	v_or_b32_e32 v52, 3, v173
	v_cmp_lt_u32_e64 s[42:43], v52, v166
	v_cmp_le_u32_e64 s[44:45], v52, v166
	v_writelane_b32 v250, s6, 42
	v_cndmask_b32_e64 v52, 0, 1, s[42:43]
	v_cndmask_b32_e64 v54, 0, 1, s[44:45]
	v_cndmask_b32_e32 v52, v54, v52, vcc
	v_and_b32_e32 v52, 1, v52
	v_writelane_b32 v250, s7, 43
	v_cmp_eq_u32_e64 s[6:7], 1, v52
	v_or_b32_e32 v52, 48, v173
	v_cmp_lt_u32_e64 s[44:45], v52, v49
	v_cmp_le_u32_e64 s[46:47], v52, v49
	v_mad_u32_u24 v189, v49, s73, v55
	v_cndmask_b32_e64 v54, 0, 1, s[44:45]
	v_cndmask_b32_e64 v55, 0, 1, s[46:47]
	v_cndmask_b32_e32 v54, v55, v54, vcc
	v_writelane_b32 v250, s6, 44
	v_and_b32_e32 v54, 1, v54
	s_mov_b32 s25, s50
	v_writelane_b32 v250, s7, 45
	v_cmp_eq_u32_e64 s[6:7], 1, v54
	v_or_b32_e32 v54, 49, v173
	v_cmp_lt_u32_e64 s[46:47], v54, v49
	v_cmp_le_u32_e64 s[48:49], v54, v49
	v_writelane_b32 v250, s6, 46
	v_cndmask_b32_e64 v54, 0, 1, s[46:47]
	v_cndmask_b32_e64 v55, 0, 1, s[48:49]
	v_cndmask_b32_e32 v54, v55, v54, vcc
	v_and_b32_e32 v54, 1, v54
	v_writelane_b32 v250, s7, 47
	v_cmp_eq_u32_e64 s[6:7], 1, v54
	v_or_b32_e32 v54, 50, v173
	v_cmp_lt_u32_e64 s[48:49], v54, v49
	s_mov_b32 s24, s51
	v_cmp_le_u32_e64 s[50:51], v54, v49
	v_cndmask_b32_e64 v54, 0, 1, s[48:49]
	v_writelane_b32 v250, s6, 48
	v_cndmask_b32_e64 v55, 0, 1, s[50:51]
	v_cndmask_b32_e32 v54, v55, v54, vcc
	v_and_b32_e32 v54, 1, v54
	v_writelane_b32 v250, s7, 49
	v_cmp_eq_u32_e64 s[6:7], 1, v54
	v_or_b32_e32 v54, 51, v173
	v_cmp_lt_u32_e64 s[50:51], v54, v49
	v_cmp_le_u32_e64 s[52:53], v54, v49
	v_writelane_b32 v250, s6, 50
	v_cndmask_b32_e64 v49, 0, 1, s[50:51]
	v_cndmask_b32_e64 v54, 0, 1, s[52:53]
	v_cndmask_b32_e32 v49, v54, v49, vcc
	v_and_b32_e32 v49, 1, v49
	v_writelane_b32 v250, s7, 51
	v_cmp_eq_u32_e64 s[6:7], 1, v49
	v_lshlrev_b32_e32 v49, 1, v52
	v_add_u32_e32 v57, 0, v28
	v_writelane_b32 v250, s6, 52
	v_lshl_or_b32 v52, s54, 5, v166
	v_mul_u32_u24_e32 v58, 0x90, v52
	v_writelane_b32 v250, s7, 53
	s_movk_i32 s7, 0x9c
	v_or_b32_e32 v52, 16, v52
	v_mad_u32_u24 v60, v166, s7, v57
	s_movk_i32 s7, 0x480
	v_mul_u32_u24_e32 v59, 0x90, v52
	v_mad_u32_u24 v52, v171, s7, 0
	s_and_b32 s7, s24, 0xffffffc0
	s_lshl_b32 s26, s0, 4
	v_add3_u32 v191, v52, s7, v28
	v_lshlrev_b32_e32 v28, 9, v171
	v_or_b32_e32 v168, s26, v166
	s_movk_i32 s6, 0x90
	v_writelane_b32 v250, s24, 54
	v_sub_u32_e32 v28, v52, v28
	v_lshl_add_u32 v62, s25, 5, v28
	v_writelane_b32 v250, s55, 55
	v_mul_lo_u32 v28, v168, s6
	s_add_i32 s6, 0, 0x20400
	s_add_i32 s93, 0, 0x1b800
	s_add_i32 s40, 0, 0x12000
	s_and_b32 s7, s92, 2
	s_add_i32 s24, 0, 0x1dc00
	v_add_u32_e32 v193, s6, v110
	s_add_i32 s6, s26, 64
	s_add_i32 s41, 0, 0x19400
	s_add_i32 s42, 0, 0x17000
	v_writelane_b32 v250, s25, 56
	s_bitcmp1_b32 s25, 0
	v_writelane_b32 v250, s26, 57
	v_or_b32_e32 v73, s26, v173
	s_movk_i32 s43, 0x120
	v_add_u32_e32 v66, s93, v28
	v_or_b32_e32 v52, s6, v166
	v_add_u32_e32 v68, s42, v28
	v_add_u32_e32 v69, s41, v28
	v_lshl_or_b32 v70, s7, 4, v166
	s_cselect_b64 s[62:63], -1, 0
	s_lshl_b32 s6, s7, 10
	v_lshl_or_b32 v169, s0, 8, v188
	s_or_b32 s0, s7, 1
	v_mul_lo_u32 v28, v73, s43
	v_writelane_b32 v250, s54, 58
	s_lshl_b32 s7, s54, 7
	v_add_u32_e32 v192, s24, v110
	s_add_i32 s24, 0, 0x22c00
	v_lshl_or_b32 v71, s0, 4, v166
	s_lshl_b32 s0, s0, 10
	v_add3_u32 v202, v57, v28, s7
	v_lshlrev_b32_e32 v28, 1, v73
	s_mov_b32 s7, 0x1ffffff0
	v_readlane_b32 s26, v250, 19
	v_and_or_b32 v57, v28, s7, v166
	v_readlane_b32 s27, v250, 20
	s_add_u32 s38, s66, 0x1000
	v_add_u32_e32 v203, 0, v28
	v_lshl_add_u64 v[118:119], s[26:27], 0, v[28:29]
	v_lshlrev_b32_e32 v28, 3, v57
	s_addc_u32 s39, s67, 0
	v_add_u32_e32 v114, s6, v169
	v_add_u32_e32 v57, s6, v28
	s_add_u32 s6, s68, 0x800
	s_addc_u32 s7, s69, 0
	v_or_b32_e32 v120, v57, v72
	v_or_b32_e32 v57, 1, v73
	v_cmp_eq_u32_e64 s[52:53], v73, v70
	v_add_u32_e32 v28, s0, v28
	v_writelane_b32 v250, s6, 59
	v_cmp_eq_u32_e32 vcc, v57, v70
	v_cndmask_b32_e64 v122, 0, 1.0, s[52:53]
	v_or_b32_e32 v124, v28, v72
	v_cmp_eq_u32_e64 s[52:53], v73, v71
	v_or_b32_e32 v28, 3, v73
	v_writelane_b32 v250, s7, 60
	s_add_u32 s6, s66, 0x800
	v_cndmask_b32_e64 v123, 0, 1.0, vcc
	v_cmp_eq_u32_e32 vcc, v57, v71
	v_cndmask_b32_e64 v126, 0, 1.0, s[52:53]
	v_or_b32_e32 v57, 2, v73
	v_cmp_eq_u32_e64 s[52:53], v28, v70
	s_addc_u32 s7, s67, 0
	v_mad_u32_u24 v26, v111, s73, 0
	v_lshlrev_b32_e32 v27, 4, v27
	v_mul_lo_u32 v186, v168, s73
	v_mul_lo_u32 v52, v52, s73
	v_cndmask_b32_e64 v127, 0, 1.0, vcc
	v_cmp_eq_u32_e32 vcc, v57, v70
	v_cndmask_b32_e64 v129, 0, 1.0, s[52:53]
	v_cmp_eq_u32_e64 s[52:53], v28, v71
	v_writelane_b32 v250, s6, 61
	v_lshlrev_b32_e32 v28, 5, v0
	v_add_u32_e32 v50, 0xa00, v183
	v_add_u32_e32 v56, 0x1400, v183
	v_add_u32_e32 v55, 0, v186
	v_add_u32_e32 v190, s93, v110
	v_add_u32_e32 v64, s40, v185
	v_add_u32_e32 v65, s40, v186
	v_add_u32_e32 v67, s40, v52
	v_lshlrev_b32_e32 v52, 6, v70
	v_lshlrev_b32_e32 v54, 6, v71
	v_add_u32_e32 v116, s0, v169
	v_cndmask_b32_e64 v128, 0, 1.0, vcc
	v_cmp_eq_u32_e32 vcc, v57, v71
	v_writelane_b32 v250, s7, 62
	s_add_u32 s6, s68, 0x1000
	v_and_b32_e32 v28, 0x3800, v28
	v_add_u32_e32 v206, v26, v27
	v_add_u32_e32 v207, v181, v46
	v_mbcnt_lo_u32_b32 v26, -1, 0
	v_mov_b32_e32 v46, 0
	v_add_u32_e32 v194, s41, v110
	v_add_u32_e32 v195, s40, v110
	v_mul_u32_u24_e32 v196, 0xa0, v70
	v_mul_u32_u24_e32 v197, 0x90, v70
	v_lshl_add_u32 v198, v70, 2, s24
	v_ashrrev_i32_e32 v115, 31, v114
	v_mul_u32_u24_e32 v199, 0xa0, v71
	v_mul_u32_u24_e32 v200, 0x90, v71
	v_lshl_add_u32 v201, v71, 2, s24
	v_ashrrev_i32_e32 v117, 31, v116
	v_lshl_add_u32 v204, v73, 2, s24
	v_ashrrev_i32_e32 v121, 31, v120
	v_ashrrev_i32_e32 v125, 31, v124
	v_cndmask_b32_e64 v131, 0, 1.0, s[52:53]
	v_cndmask_b32_e64 v130, 0, 1.0, vcc
	s_addc_u32 s7, s69, 0
	v_lshl_add_u64 v[132:133], s[70:71], 0, v[28:29]
	s_mov_b32 s34, -1
	s_movk_i32 s71, 0x630
	s_mov_b32 s44, 0x3e0f83e1
	s_movk_i32 s45, 0xfdf0
	s_movk_i32 s46, 0x2940
	s_mov_b32 s47, 0x5040100
	s_mov_b32 s70, 0xbf60033a
	v_mbcnt_hi_u32_b32 v208, -1, v26
	s_add_i32 s48, 0, 0x12280
	s_movk_i32 s49, 0x2600
	v_add_u32_e32 v209, v50, v172
	v_add_u32_e32 v210, v51, v110
	v_add_u32_e32 v211, v53, v110
	v_add_u32_e32 v212, v189, v49
	v_add_u32_e32 v213, v60, v172
	v_add_u32_e32 v214, v62, v61
	v_add_u32_e32 v216, v64, v172
	v_add_u32_e32 v217, v65, v110
	v_lshlrev_b32_e32 v134, 1, v52
	v_add_u32_e32 v218, v68, v110
	v_add_u32_e32 v219, v69, v110
	v_lshlrev_b32_e32 v136, 1, v54
	v_add_u32_e32 v221, v47, v110
	v_add_u32_e32 v222, v48, v110
	v_add_u32_e32 v223, v56, v172
	v_mov_b32_e32 v139, v46
	v_add_u32_e32 v224, v55, v110
	v_add_u32_e32 v225, v190, v58
	v_add_u32_e32 v226, v190, v59
	v_add_u32_e32 v227, v66, v110
	v_add_u32_e32 v228, v67, v110
	s_mov_b32 s51, 0
	v_lshrrev_b32_e32 v26, 3, v0
	v_and_b32_e32 v27, 7, v0
	v_mul_u32_u24_e32 v26, 0x2600, v26
	v_lshl_add_u32 v251, v27, 4, v26
	v_mov_b32_e32 v26, v0
	v_lshrrev_b32_e32 v27, 4, v26
	v_mul_u32_u24_e32 v27, 0x7c2, v27
	v_lshrrev_b32_e32 v27, 16, v27
	v_mul_u32_u24_e32 v28, 0x210, v27
	v_sub_u32_e32 v26, v26, v28
	v_lshrrev_b32_e32 v28, 3, v26
	v_and_b32_e32 v26, 7, v26
	v_mul_u32_u24_e32 v28, 0x2600, v28
	v_lshl_add_u32 v28, v27, 10, v28
	v_lshl_add_u32 v252, v26, 4, v28
	v_add_u32_e32 v26, 0x200, v0
	v_lshrrev_b32_e32 v27, 4, v26
	v_mul_u32_u24_e32 v27, 0x7c2, v27
	v_lshrrev_b32_e32 v27, 16, v27
	v_mul_u32_u24_e32 v28, 0x210, v27
	v_sub_u32_e32 v26, v26, v28
	v_lshrrev_b32_e32 v28, 3, v26
	v_and_b32_e32 v26, 7, v26
	v_mul_u32_u24_e32 v28, 0x2600, v28
	v_lshl_add_u32 v28, v27, 10, v28
	v_lshl_add_u32 v253, v26, 4, v28
	v_add_u32_e32 v26, 0x400, v0
	v_lshrrev_b32_e32 v27, 4, v26
	v_mul_u32_u24_e32 v27, 0x7c2, v27
	v_lshrrev_b32_e32 v27, 16, v27
	v_mul_u32_u24_e32 v28, 0x210, v27
	v_sub_u32_e32 v26, v26, v28
	v_lshrrev_b32_e32 v28, 3, v26
	v_and_b32_e32 v26, 7, v26
	v_mul_u32_u24_e32 v28, 0x2600, v28
	v_lshl_add_u32 v28, v27, 10, v28
	v_lshl_add_u32 v254, v26, 4, v28
	v_add_u32_e32 v26, 0x600, v0
	v_lshrrev_b32_e32 v27, 4, v26
	v_mul_u32_u24_e32 v27, 0x7c2, v27
	v_lshrrev_b32_e32 v27, 16, v27
	v_mul_u32_u24_e32 v28, 0x210, v27
	v_sub_u32_e32 v26, v26, v28
	v_lshrrev_b32_e32 v28, 3, v26
	v_and_b32_e32 v26, 7, v26
	v_mul_u32_u24_e32 v28, 0x2600, v28
	v_lshl_add_u32 v28, v27, 10, v28
	v_lshl_add_u32 v255, v26, 4, v28
	s_branch .LBB0_295

.LBB0_403:
	v_readlane_b32 s2, v250, 16
	v_readlane_b32 s3, v250, 17
	s_mov_b64 s[0:1], -1
	s_and_b64 vcc, exec, s[2:3]
	v_readlane_b32 s50, v250, 56
	v_readlane_b32 s51, v250, 54
	s_cbranch_vccz .LBB0_439
	s_mov_b64 exec, -1
	s_waitcnt vmcnt(0) lgkmcnt(0)
	v_readlane_b32 s0, v250, 18
	v_readfirstlane_b32 s6, v0
	v_and_b32_e32 v1, 63, v0
	s_lshr_b32 s6, s6, 6
	s_ashr_i32 s1, s0, 2
	s_and_b32 s2, s0, 3
	s_and_b32 s3, s1, 3
	s_bfe_u32 s4, s1, 0x20002
	s_lshr_b32 s5, s1, 4
	v_lshlrev_b32_e32 v2, 2, v0
	v_add_u32_e32 v2, 0x1e800, v2
	v_mov_b32_e32 v3, 0
	ds_write_b32 v2, v3
	ds_write_b32 v2, v3 offset:2048
	ds_write_b32 v2, v3 offset:4096
	ds_write_b32 v2, v3 offset:6144
	ds_write_b32 v2, v3 offset:8192
	s_cmp_eq_u32 s5, 0
	s_cselect_b64 s[36:37], -1, 0
	s_cmp_lt_u32 s6, 4
	s_cbranch_scc0 .Lhg_sinit
	v_and_b32_e32 v20, 7, v1
	v_lshrrev_b32_e32 v21, 3, v1
	s_lshl_b32 s7, s6, 5
	v_lshl_add_u32 v22, v20, 2, s7
	v_lshlrev_b32_e32 v23, 3, v21
	v_sub_u32_e32 v24, 0xfff, v23
	s_mov_b64 vcc, s[36:37]
	v_cndmask_b32_e32 v23, v24, v23, vcc
	v_mul_u32_u24_e32 v2, 0x2600, v23
	v_lshl_add_u32 v2, v22, 1, v2
	s_lshl_b32 s7, s5, 10
	s_add_i32 s7, s7, 0x400
	v_add_u32_e32 v3, s7, v2
	s_mul_i32 s7, s4, 0x2600000
	s_lshl_b32 s8, s3, 8
	s_add_i32 s7, s7, s8
	s_add_i32 s7, s7, 0x101200
	s_add_u32 s8, s98, s7
	s_addc_u32 s9, s99, 0
	s_lshl_b32 s7, s5, 1
	s_sub_i32 s7, 1, s7
	s_mul_i32 s10, s7, 0x2600
	s_ashr_i32 s11, s10, 31
	s_mul_i32 s12, s7, 0x85000
	s_ashr_i32 s13, s12, 31
	s_mul_i32 s14, s7, 0xfffed000
	s_ashr_i32 s15, s14, 31
	s_mov_b32 s16, 0
	v_mul_u32_u24_e32 v4, 0x900, v21
	v_lshl_add_u32 v4, v22, 1, v4
	v_xor_b32_e32 v5, v21, v20
	v_lshlrev_b32_e32 v5, 4, v5
	v_mul_u32_u24_e32 v24, 0xa0, v22
	v_add_u32_e32 v5, v5, v24
	v_add_u32_e32 v5, 0x12000, v5
	s_lshl_b32 s7, s6, 10
	v_lshl_add_u32 v7, v20, 4, s7
	v_add_u32_e32 v7, 0x24400, v7
	v_lshl_add_u32 v6, v21, 7, v7
	v_lshlrev_b32_e32 v8, 2, v22
	v_add_u32_e32 v8, 0x24000, v8
	s_mov_b64 s[18:19], -1
	s_lshl_b64 s[18:19], s[18:19], 8
	s_mov_b64 s[20:21], -1
	s_lshl_b64 s[20:21], s[20:21], 16
	s_mov_b64 s[22:23], -1
	s_lshl_b64 s[22:23], s[22:23], 24
	s_mov_b64 s[24:25], -1
	s_lshl_b64 s[24:25], s[24:25], 32
	s_mov_b64 s[26:27], -1
	s_lshl_b64 s[26:27], s[26:27], 40
	s_mov_b64 s[28:29], -1
	s_lshl_b64 s[28:29], s[28:29], 48
	s_mov_b64 s[30:31], -1
	s_lshl_b64 s[30:31], s[30:31], 56
	global_load_dwordx2 v[10:11], v3, s[8:9]
	global_load_dwordx2 v[26:27], v2, s[8:9]
	s_add_u32 s8, s8, s10
	s_addc_u32 s9, s9, s11
	global_load_dwordx2 v[12:13], v3, s[8:9]
	global_load_dwordx2 v[28:29], v2, s[8:9]
	s_add_u32 s8, s8, s10
	s_addc_u32 s9, s9, s11
	global_load_dwordx2 v[14:15], v3, s[8:9]
	global_load_dwordx2 v[30:31], v2, s[8:9]
	s_add_u32 s8, s8, s10
	s_addc_u32 s9, s9, s11
	global_load_dwordx2 v[16:17], v3, s[8:9]
	global_load_dwordx2 v[32:33], v2, s[8:9]
	s_add_u32 s8, s8, s10
	s_addc_u32 s9, s9, s11
	global_load_dwordx2 v[18:19], v3, s[8:9]
	global_load_dwordx2 v[34:35], v2, s[8:9]
	s_add_u32 s8, s8, s10
	s_addc_u32 s9, s9, s11
	global_load_dwordx2 v[20:21], v3, s[8:9]
	global_load_dwordx2 v[36:37], v2, s[8:9]
	s_add_u32 s8, s8, s10
	s_addc_u32 s9, s9, s11
	global_load_dwordx2 v[22:23], v3, s[8:9]
	global_load_dwordx2 v[38:39], v2, s[8:9]
	s_add_u32 s8, s8, s10
	s_addc_u32 s9, s9, s11
	global_load_dwordx2 v[24:25], v3, s[8:9]
	global_load_dwordx2 v[40:41], v2, s[8:9]
	s_add_u32 s8, s8, s10
	s_addc_u32 s9, s9, s11
	s_cmp_lt_u32 s16, 63
	s_cselect_b32 s34, s12, s14
	s_cselect_b32 s35, s13, s15
	s_add_u32 s8, s8, s34
	s_addc_u32 s9, s9, s35
	s_add_i32 s16, s16, 1
	global_load_dwordx2 v[42:43], v3, s[8:9]
	global_load_dwordx2 v[58:59], v2, s[8:9]
	s_add_u32 s8, s8, s10
	s_addc_u32 s9, s9, s11
	global_load_dwordx2 v[44:45], v3, s[8:9]
	global_load_dwordx2 v[60:61], v2, s[8:9]
	s_add_u32 s8, s8, s10
	s_addc_u32 s9, s9, s11
	global_load_dwordx2 v[46:47], v3, s[8:9]
	global_load_dwordx2 v[62:63], v2, s[8:9]
	s_add_u32 s8, s8, s10
	s_addc_u32 s9, s9, s11
	global_load_dwordx2 v[48:49], v3, s[8:9]
	global_load_dwordx2 v[64:65], v2, s[8:9]
	s_add_u32 s8, s8, s10
	s_addc_u32 s9, s9, s11
	global_load_dwordx2 v[50:51], v3, s[8:9]
	global_load_dwordx2 v[66:67], v2, s[8:9]
	s_add_u32 s8, s8, s10
	s_addc_u32 s9, s9, s11
	global_load_dwordx2 v[52:53], v3, s[8:9]
	global_load_dwordx2 v[68:69], v2, s[8:9]
	s_add_u32 s8, s8, s10
	s_addc_u32 s9, s9, s11
	global_load_dwordx2 v[54:55], v3, s[8:9]
	global_load_dwordx2 v[70:71], v2, s[8:9]
	s_add_u32 s8, s8, s10
	s_addc_u32 s9, s9, s11
	global_load_dwordx2 v[56:57], v3, s[8:9]
	global_load_dwordx2 v[72:73], v2, s[8:9]
	s_add_u32 s8, s8, s10
	s_addc_u32 s9, s9, s11
	s_cmp_lt_u32 s16, 63
	s_cselect_b32 s34, s12, s14
	s_cselect_b32 s35, s13, s15
	s_add_u32 s8, s8, s34
	s_addc_u32 s9, s9, s35
	s_add_i32 s16, s16, 1
	s_waitcnt vmcnt(0)
	s_waitcnt lgkmcnt(0)
	s_barrier
	s_mov_b64 s[38:39], exec
	v_readlane_b32 s40, v250, 10
	v_readlane_b32 s41, v250, 11
	s_and_b64 s[40:41], s[38:39], s[40:41]
	s_mov_b64 exec, s[40:41]
	s_cbranch_execz .Lhg_rel0
	s_mov_b64 s[40:41], exec
	v_mbcnt_lo_u32_b32 v224, s40, 0
	buffer_wbl2 sc1
	s_waitcnt vmcnt(0)
	v_mbcnt_hi_u32_b32 v224, s41, v224
	v_cmp_eq_u32_e32 vcc, 0, v224
	s_and_b64 s[42:43], exec, vcc
	s_mov_b64 exec, s[42:43]
	s_cbranch_execz .Lhg_rel0
	s_bcnt1_i32_b64 s42, s[40:41]
	s_lshl_b32 s40, s1, 7
	s_add_u32 s40, s98, s40
	s_addc_u32 s41, s99, 0
	v_mov_b32_e32 v224, 0x2000
	v_mov_b32_e32 v225, s42
	global_atomic_add v224, v225, s[40:41]
.Lhg_rel0:
	s_or_b64 exec, exec, s[38:39]
	s_waitcnt vmcnt(16)
	v_lshlrev_b32_e32 v76, 16, v10
	v_and_b32_e32 v77, 0xffff0000, v10
	v_lshlrev_b32_e32 v78, 16, v11
	v_and_b32_e32 v79, 0xffff0000, v11
	v_lshlrev_b32_e32 v80, 16, v12
	v_and_b32_e32 v81, 0xffff0000, v12
	v_lshlrev_b32_e32 v82, 16, v13
	v_and_b32_e32 v83, 0xffff0000, v13
	v_lshlrev_b32_e32 v84, 16, v14
	v_and_b32_e32 v85, 0xffff0000, v14
	v_lshlrev_b32_e32 v86, 16, v15
	v_and_b32_e32 v87, 0xffff0000, v15
	v_lshlrev_b32_e32 v88, 16, v16
	v_and_b32_e32 v89, 0xffff0000, v16
	v_lshlrev_b32_e32 v90, 16, v17
	v_and_b32_e32 v91, 0xffff0000, v17
	v_lshlrev_b32_e32 v92, 16, v18
	v_and_b32_e32 v93, 0xffff0000, v18
	v_lshlrev_b32_e32 v94, 16, v19
	v_and_b32_e32 v95, 0xffff0000, v19
	v_lshlrev_b32_e32 v96, 16, v20
	v_and_b32_e32 v97, 0xffff0000, v20
	v_lshlrev_b32_e32 v98, 16, v21
	v_and_b32_e32 v99, 0xffff0000, v21
	v_lshlrev_b32_e32 v100, 16, v22
	v_and_b32_e32 v101, 0xffff0000, v22
	v_lshlrev_b32_e32 v102, 16, v23
	v_and_b32_e32 v103, 0xffff0000, v23
	v_lshlrev_b32_e32 v104, 16, v24
	v_and_b32_e32 v105, 0xffff0000, v24
	v_lshlrev_b32_e32 v106, 16, v25
	v_and_b32_e32 v107, 0xffff0000, v25
	v_lshlrev_b32_e32 v108, 16, v26
	v_and_b32_e32 v109, 0xffff0000, v26
	v_lshlrev_b32_e32 v110, 16, v27
	v_and_b32_e32 v111, 0xffff0000, v27
	v_lshlrev_b32_e32 v112, 16, v28
	v_and_b32_e32 v113, 0xffff0000, v28
	v_lshlrev_b32_e32 v114, 16, v29
	v_and_b32_e32 v115, 0xffff0000, v29
	v_lshlrev_b32_e32 v116, 16, v30
	v_and_b32_e32 v117, 0xffff0000, v30
	v_lshlrev_b32_e32 v118, 16, v31
	v_and_b32_e32 v119, 0xffff0000, v31
	v_lshlrev_b32_e32 v120, 16, v32
	v_and_b32_e32 v121, 0xffff0000, v32
	v_lshlrev_b32_e32 v122, 16, v33
	v_and_b32_e32 v123, 0xffff0000, v33
	v_lshlrev_b32_e32 v124, 16, v34
	v_and_b32_e32 v125, 0xffff0000, v34
	v_lshlrev_b32_e32 v126, 16, v35
	v_and_b32_e32 v127, 0xffff0000, v35
	v_lshlrev_b32_e32 v128, 16, v36
	v_and_b32_e32 v129, 0xffff0000, v36
	v_lshlrev_b32_e32 v130, 16, v37
	v_and_b32_e32 v131, 0xffff0000, v37
	v_lshlrev_b32_e32 v132, 16, v38
	v_and_b32_e32 v133, 0xffff0000, v38
	v_lshlrev_b32_e32 v134, 16, v39
	v_and_b32_e32 v135, 0xffff0000, v39
	v_lshlrev_b32_e32 v136, 16, v40
	v_and_b32_e32 v137, 0xffff0000, v40
	v_lshlrev_b32_e32 v138, 16, v41
	v_and_b32_e32 v139, 0xffff0000, v41
	global_load_dwordx2 v[10:11], v3, s[8:9]
	global_load_dwordx2 v[26:27], v2, s[8:9]
	s_add_u32 s8, s8, s10
	s_addc_u32 s9, s9, s11
	global_load_dwordx2 v[12:13], v3, s[8:9]
	global_load_dwordx2 v[28:29], v2, s[8:9]
	s_add_u32 s8, s8, s10
	s_addc_u32 s9, s9, s11
	global_load_dwordx2 v[14:15], v3, s[8:9]
	global_load_dwordx2 v[30:31], v2, s[8:9]
	s_add_u32 s8, s8, s10
	s_addc_u32 s9, s9, s11
	global_load_dwordx2 v[16:17], v3, s[8:9]
	global_load_dwordx2 v[32:33], v2, s[8:9]
	s_add_u32 s8, s8, s10
	s_addc_u32 s9, s9, s11
	global_load_dwordx2 v[18:19], v3, s[8:9]
	global_load_dwordx2 v[34:35], v2, s[8:9]
	s_add_u32 s8, s8, s10
	s_addc_u32 s9, s9, s11
	global_load_dwordx2 v[20:21], v3, s[8:9]
	global_load_dwordx2 v[36:37], v2, s[8:9]
	s_add_u32 s8, s8, s10
	s_addc_u32 s9, s9, s11
	global_load_dwordx2 v[22:23], v3, s[8:9]
	global_load_dwordx2 v[38:39], v2, s[8:9]
	s_add_u32 s8, s8, s10
	s_addc_u32 s9, s9, s11
	global_load_dwordx2 v[24:25], v3, s[8:9]
	global_load_dwordx2 v[40:41], v2, s[8:9]
	s_add_u32 s8, s8, s10
	s_addc_u32 s9, s9, s11
	s_cmp_lt_u32 s16, 63
	s_cselect_b32 s34, s12, s14
	s_cselect_b32 s35, s13, s15
	s_add_u32 s8, s8, s34
	s_addc_u32 s9, s9, s35
	s_add_i32 s16, s16, 1
	v_pk_add_f32 v[140:141], v[76:77], 1.0 op_sel_hi:[1,0] neg_lo:[1,0] neg_hi:[1,0]
	v_pk_add_f32 v[142:143], v[78:79], 1.0 op_sel_hi:[1,0] neg_lo:[1,0] neg_hi:[1,0]
	v_pk_add_f32 v[184:185], v[80:81], 1.0 op_sel_hi:[1,0] neg_lo:[1,0] neg_hi:[1,0]
	v_pk_add_f32 v[186:187], v[82:83], 1.0 op_sel_hi:[1,0] neg_lo:[1,0] neg_hi:[1,0]
	v_pk_mul_f32 v[144:145], v[140:141], v[184:185]
	v_pk_mul_f32 v[146:147], v[142:143], v[186:187]
	v_pk_add_f32 v[184:185], v[84:85], 1.0 op_sel_hi:[1,0] neg_lo:[1,0] neg_hi:[1,0]
	v_pk_add_f32 v[186:187], v[86:87], 1.0 op_sel_hi:[1,0] neg_lo:[1,0] neg_hi:[1,0]
	v_pk_mul_f32 v[148:149], v[144:145], v[184:185]
	v_pk_mul_f32 v[150:151], v[146:147], v[186:187]
	v_pk_add_f32 v[184:185], v[88:89], 1.0 op_sel_hi:[1,0] neg_lo:[1,0] neg_hi:[1,0]
	v_pk_add_f32 v[186:187], v[90:91], 1.0 op_sel_hi:[1,0] neg_lo:[1,0] neg_hi:[1,0]
	v_pk_mul_f32 v[152:153], v[148:149], v[184:185]
	v_pk_mul_f32 v[154:155], v[150:151], v[186:187]
	v_pk_add_f32 v[184:185], v[92:93], 1.0 op_sel_hi:[1,0] neg_lo:[1,0] neg_hi:[1,0]
	v_pk_add_f32 v[186:187], v[94:95], 1.0 op_sel_hi:[1,0] neg_lo:[1,0] neg_hi:[1,0]
	v_pk_mul_f32 v[156:157], v[152:153], v[184:185]
	v_pk_mul_f32 v[158:159], v[154:155], v[186:187]
	v_pk_add_f32 v[184:185], v[96:97], 1.0 op_sel_hi:[1,0] neg_lo:[1,0] neg_hi:[1,0]
	v_pk_add_f32 v[186:187], v[98:99], 1.0 op_sel_hi:[1,0] neg_lo:[1,0] neg_hi:[1,0]
	v_pk_mul_f32 v[160:161], v[156:157], v[184:185]
	v_pk_mul_f32 v[162:163], v[158:159], v[186:187]
	v_pk_add_f32 v[184:185], v[100:101], 1.0 op_sel_hi:[1,0] neg_lo:[1,0] neg_hi:[1,0]
	v_pk_add_f32 v[186:187], v[102:103], 1.0 op_sel_hi:[1,0] neg_lo:[1,0] neg_hi:[1,0]
	v_pk_mul_f32 v[164:165], v[160:161], v[184:185]
	v_pk_mul_f32 v[166:167], v[162:163], v[186:187]
	v_pk_add_f32 v[184:185], v[104:105], 1.0 op_sel_hi:[1,0] neg_lo:[1,0] neg_hi:[1,0]
	v_pk_add_f32 v[186:187], v[106:107], 1.0 op_sel_hi:[1,0] neg_lo:[1,0] neg_hi:[1,0]
	v_pk_mul_f32 v[168:169], v[164:165], v[184:185]
	v_pk_mul_f32 v[170:171], v[166:167], v[186:187]
	ds_write_b128 v6, v[168:171]
	ds_read_b128 v[192:195], v7
	ds_read_b128 v[196:199], v7 offset:128
	ds_read_b128 v[200:203], v7 offset:256
	ds_read_b128 v[204:207], v7 offset:384
	ds_read_b128 v[208:211], v7 offset:512
	ds_read_b128 v[212:215], v7 offset:640
	ds_read_b128 v[216:219], v7 offset:768
	s_waitcnt lgkmcnt(6)
	v_cndmask_b32_e64 v192, 1.0, v192, s[18:19]
	v_cndmask_b32_e64 v193, 1.0, v193, s[18:19]
	v_cndmask_b32_e64 v194, 1.0, v194, s[18:19]
	v_cndmask_b32_e64 v195, 1.0, v195, s[18:19]
	s_waitcnt lgkmcnt(5)
	v_cndmask_b32_e64 v196, 1.0, v196, s[20:21]
	v_cndmask_b32_e64 v197, 1.0, v197, s[20:21]
	v_cndmask_b32_e64 v198, 1.0, v198, s[20:21]
	v_cndmask_b32_e64 v199, 1.0, v199, s[20:21]
	s_waitcnt lgkmcnt(4)
	v_cndmask_b32_e64 v200, 1.0, v200, s[22:23]
	v_cndmask_b32_e64 v201, 1.0, v201, s[22:23]
	v_cndmask_b32_e64 v202, 1.0, v202, s[22:23]
	v_cndmask_b32_e64 v203, 1.0, v203, s[22:23]
	s_waitcnt lgkmcnt(3)
	v_cndmask_b32_e64 v204, 1.0, v204, s[24:25]
	v_cndmask_b32_e64 v205, 1.0, v205, s[24:25]
	v_cndmask_b32_e64 v206, 1.0, v206, s[24:25]
	v_cndmask_b32_e64 v207, 1.0, v207, s[24:25]
	s_waitcnt lgkmcnt(2)
	v_cndmask_b32_e64 v208, 1.0, v208, s[26:27]
	v_cndmask_b32_e64 v209, 1.0, v209, s[26:27]
	v_cndmask_b32_e64 v210, 1.0, v210, s[26:27]
	v_cndmask_b32_e64 v211, 1.0, v211, s[26:27]
	s_waitcnt lgkmcnt(1)
	v_cndmask_b32_e64 v212, 1.0, v212, s[28:29]
	v_cndmask_b32_e64 v213, 1.0, v213, s[28:29]
	v_cndmask_b32_e64 v214, 1.0, v214, s[28:29]
	v_cndmask_b32_e64 v215, 1.0, v215, s[28:29]
	s_waitcnt lgkmcnt(0)
	v_cndmask_b32_e64 v216, 1.0, v216, s[30:31]
	v_cndmask_b32_e64 v217, 1.0, v217, s[30:31]
	v_cndmask_b32_e64 v218, 1.0, v218, s[30:31]
	v_cndmask_b32_e64 v219, 1.0, v219, s[30:31]
	v_pk_mul_f32 v[192:193], v[192:193], v[196:197]
	v_pk_mul_f32 v[194:195], v[194:195], v[198:199]
	v_pk_mul_f32 v[200:201], v[200:201], v[204:205]
	v_pk_mul_f32 v[202:203], v[202:203], v[206:207]
	v_pk_mul_f32 v[208:209], v[208:209], v[212:213]
	v_pk_mul_f32 v[210:211], v[210:211], v[214:215]
	v_pk_mul_f32 v[192:193], v[192:193], v[200:201]
	v_pk_mul_f32 v[194:195], v[194:195], v[202:203]
	v_pk_mul_f32 v[208:209], v[208:209], v[216:217]
	v_pk_mul_f32 v[210:211], v[210:211], v[218:219]
	v_pk_mul_f32 v[176:177], v[192:193], v[208:209]
	v_pk_mul_f32 v[178:179], v[194:195], v[210:211]
	v_pk_mul_f32 v[188:189], v[176:177], v[168:169]
	v_pk_mul_f32 v[190:191], v[178:179], v[170:171]
	s_mov_b64 s[34:35], exec
	s_mov_b64 exec, s[30:31]
	ds_write_b128 v8, v[188:191]
	s_mov_b64 exec, s[34:35]
	v_max_f32_e32 v180, 0xda24260, v188
	v_max_f32_e32 v181, 0xda24260, v189
	v_max_f32_e32 v182, 0xda24260, v190
	v_max_f32_e32 v183, 0xda24260, v191
	v_rcp_f32_e32 v180, v180
	v_rcp_f32_e32 v181, v181
	v_rcp_f32_e32 v182, v182
	v_rcp_f32_e32 v183, v183
	v_pk_mul_f32 v[192:193], v[136:137], v[188:189]
	v_pk_mul_f32 v[194:195], v[138:139], v[190:191]
	v_pk_mul_f32 v[196:197], v[104:105], v[180:181]
	v_pk_mul_f32 v[198:199], v[106:107], v[182:183]
	v_cvt_pk_bf16_f32 v204, v192, v193
	v_cvt_pk_bf16_f32 v205, v194, v195
	ds_write_b64 v4, v[204:205] offset:2016
	v_cvt_pk_bf16_f32 v206, v196, v197
	v_cvt_pk_bf16_f32 v207, v198, v199
	ds_write_b64 v4, v[206:207] offset:38880
	v_pk_add_f32 v[184:185], v[104:105], 1.0 op_sel_hi:[1,0] neg_lo:[1,0] neg_hi:[1,0]
	v_pk_add_f32 v[186:187], v[106:107], 1.0 op_sel_hi:[1,0] neg_lo:[1,0] neg_hi:[1,0]
	v_pk_mul_f32 v[180:181], v[180:181], v[184:185]
	v_pk_mul_f32 v[182:183], v[182:183], v[186:187]
	v_pk_mul_f32 v[188:189], v[176:177], v[164:165]
	v_pk_mul_f32 v[190:191], v[178:179], v[166:167]
	v_pk_mul_f32 v[192:193], v[132:133], v[188:189]
	v_pk_mul_f32 v[194:195], v[134:135], v[190:191]
	v_pk_mul_f32 v[200:201], v[100:101], v[180:181]
	v_pk_mul_f32 v[202:203], v[102:103], v[182:183]
	v_cvt_pk_bf16_f32 v204, v192, v193
	v_cvt_pk_bf16_f32 v205, v194, v195
	ds_write_b64 v4, v[204:205] offset:1728
	v_cvt_pk_bf16_f32 v206, v200, v201
	v_cvt_pk_bf16_f32 v207, v202, v203
	ds_write_b64 v4, v[206:207] offset:38592
	v_cvt_pk_bf16_f32 v211, v200, v196
	v_cvt_pk_bf16_f32 v215, v201, v197
	v_cvt_pk_bf16_f32 v219, v202, v198
	v_cvt_pk_bf16_f32 v223, v203, v199
	v_pk_add_f32 v[184:185], v[100:101], 1.0 op_sel_hi:[1,0] neg_lo:[1,0] neg_hi:[1,0]
	v_pk_add_f32 v[186:187], v[102:103], 1.0 op_sel_hi:[1,0] neg_lo:[1,0] neg_hi:[1,0]
	v_pk_mul_f32 v[180:181], v[180:181], v[184:185]
	v_pk_mul_f32 v[182:183], v[182:183], v[186:187]
	v_pk_mul_f32 v[188:189], v[176:177], v[160:161]
	v_pk_mul_f32 v[190:191], v[178:179], v[162:163]
	v_pk_mul_f32 v[192:193], v[128:129], v[188:189]
	v_pk_mul_f32 v[194:195], v[130:131], v[190:191]
	v_pk_mul_f32 v[196:197], v[96:97], v[180:181]
	v_pk_mul_f32 v[198:199], v[98:99], v[182:183]
	v_cvt_pk_bf16_f32 v204, v192, v193
	v_cvt_pk_bf16_f32 v205, v194, v195
	ds_write_b64 v4, v[204:205] offset:1440
	v_cvt_pk_bf16_f32 v206, v196, v197
	v_cvt_pk_bf16_f32 v207, v198, v199
	ds_write_b64 v4, v[206:207] offset:38304
	v_pk_add_f32 v[184:185], v[96:97], 1.0 op_sel_hi:[1,0] neg_lo:[1,0] neg_hi:[1,0]
	v_pk_add_f32 v[186:187], v[98:99], 1.0 op_sel_hi:[1,0] neg_lo:[1,0] neg_hi:[1,0]
	v_pk_mul_f32 v[180:181], v[180:181], v[184:185]
	v_pk_mul_f32 v[182:183], v[182:183], v[186:187]
	v_pk_mul_f32 v[188:189], v[176:177], v[156:157]
	v_pk_mul_f32 v[190:191], v[178:179], v[158:159]
	v_pk_mul_f32 v[192:193], v[124:125], v[188:189]
	v_pk_mul_f32 v[194:195], v[126:127], v[190:191]
	v_pk_mul_f32 v[200:201], v[92:93], v[180:181]
	v_pk_mul_f32 v[202:203], v[94:95], v[182:183]
	v_cvt_pk_bf16_f32 v204, v192, v193
	v_cvt_pk_bf16_f32 v205, v194, v195
	ds_write_b64 v4, v[204:205] offset:1152
	v_cvt_pk_bf16_f32 v206, v200, v201
	v_cvt_pk_bf16_f32 v207, v202, v203
	ds_write_b64 v4, v[206:207] offset:38016
	v_cvt_pk_bf16_f32 v210, v200, v196
	v_cvt_pk_bf16_f32 v214, v201, v197
	v_cvt_pk_bf16_f32 v218, v202, v198
	v_cvt_pk_bf16_f32 v222, v203, v199
	v_pk_add_f32 v[184:185], v[92:93], 1.0 op_sel_hi:[1,0] neg_lo:[1,0] neg_hi:[1,0]
	v_pk_add_f32 v[186:187], v[94:95], 1.0 op_sel_hi:[1,0] neg_lo:[1,0] neg_hi:[1,0]
	v_pk_mul_f32 v[180:181], v[180:181], v[184:185]
	v_pk_mul_f32 v[182:183], v[182:183], v[186:187]
	v_pk_mul_f32 v[188:189], v[176:177], v[152:153]
	v_pk_mul_f32 v[190:191], v[178:179], v[154:155]
	v_pk_mul_f32 v[192:193], v[120:121], v[188:189]
	v_pk_mul_f32 v[194:195], v[122:123], v[190:191]
	v_pk_mul_f32 v[196:197], v[88:89], v[180:181]
	v_pk_mul_f32 v[198:199], v[90:91], v[182:183]
	v_cvt_pk_bf16_f32 v204, v192, v193
	v_cvt_pk_bf16_f32 v205, v194, v195
	ds_write_b64 v4, v[204:205] offset:864
	v_cvt_pk_bf16_f32 v206, v196, v197
	v_cvt_pk_bf16_f32 v207, v198, v199
	ds_write_b64 v4, v[206:207] offset:37728
	v_pk_add_f32 v[184:185], v[88:89], 1.0 op_sel_hi:[1,0] neg_lo:[1,0] neg_hi:[1,0]
	v_pk_add_f32 v[186:187], v[90:91], 1.0 op_sel_hi:[1,0] neg_lo:[1,0] neg_hi:[1,0]
	v_pk_mul_f32 v[180:181], v[180:181], v[184:185]
	v_pk_mul_f32 v[182:183], v[182:183], v[186:187]
	v_pk_mul_f32 v[188:189], v[176:177], v[148:149]
	v_pk_mul_f32 v[190:191], v[178:179], v[150:151]
	v_pk_mul_f32 v[192:193], v[116:117], v[188:189]
	v_pk_mul_f32 v[194:195], v[118:119], v[190:191]
	v_pk_mul_f32 v[200:201], v[84:85], v[180:181]
	v_pk_mul_f32 v[202:203], v[86:87], v[182:183]
	v_cvt_pk_bf16_f32 v204, v192, v193
	v_cvt_pk_bf16_f32 v205, v194, v195
	ds_write_b64 v4, v[204:205] offset:576
	v_cvt_pk_bf16_f32 v206, v200, v201
	v_cvt_pk_bf16_f32 v207, v202, v203
	ds_write_b64 v4, v[206:207] offset:37440
	v_cvt_pk_bf16_f32 v209, v200, v196
	v_cvt_pk_bf16_f32 v213, v201, v197
	v_cvt_pk_bf16_f32 v217, v202, v198
	v_cvt_pk_bf16_f32 v221, v203, v199
	v_pk_add_f32 v[184:185], v[84:85], 1.0 op_sel_hi:[1,0] neg_lo:[1,0] neg_hi:[1,0]
	v_pk_add_f32 v[186:187], v[86:87], 1.0 op_sel_hi:[1,0] neg_lo:[1,0] neg_hi:[1,0]
	v_pk_mul_f32 v[180:181], v[180:181], v[184:185]
	v_pk_mul_f32 v[182:183], v[182:183], v[186:187]
	v_pk_mul_f32 v[188:189], v[176:177], v[144:145]
	v_pk_mul_f32 v[190:191], v[178:179], v[146:147]
	v_pk_mul_f32 v[192:193], v[112:113], v[188:189]
	v_pk_mul_f32 v[194:195], v[114:115], v[190:191]
	v_pk_mul_f32 v[196:197], v[80:81], v[180:181]
	v_pk_mul_f32 v[198:199], v[82:83], v[182:183]
	v_cvt_pk_bf16_f32 v204, v192, v193
	v_cvt_pk_bf16_f32 v205, v194, v195
	ds_write_b64 v4, v[204:205] offset:288
	v_cvt_pk_bf16_f32 v206, v196, v197
	v_cvt_pk_bf16_f32 v207, v198, v199
	ds_write_b64 v4, v[206:207] offset:37152
	v_pk_add_f32 v[184:185], v[80:81], 1.0 op_sel_hi:[1,0] neg_lo:[1,0] neg_hi:[1,0]
	v_pk_add_f32 v[186:187], v[82:83], 1.0 op_sel_hi:[1,0] neg_lo:[1,0] neg_hi:[1,0]
	v_pk_mul_f32 v[180:181], v[180:181], v[184:185]
	v_pk_mul_f32 v[182:183], v[182:183], v[186:187]
	v_pk_mul_f32 v[188:189], v[176:177], v[140:141]
	v_pk_mul_f32 v[190:191], v[178:179], v[142:143]
	v_pk_mul_f32 v[192:193], v[108:109], v[188:189]
	v_pk_mul_f32 v[194:195], v[110:111], v[190:191]
	v_pk_mul_f32 v[200:201], v[76:77], v[180:181]
	v_pk_mul_f32 v[202:203], v[78:79], v[182:183]
	v_cvt_pk_bf16_f32 v204, v192, v193
	v_cvt_pk_bf16_f32 v205, v194, v195
	ds_write_b64 v4, v[204:205]
	v_cvt_pk_bf16_f32 v206, v200, v201
	v_cvt_pk_bf16_f32 v207, v202, v203
	ds_write_b64 v4, v[206:207] offset:36864
	v_cvt_pk_bf16_f32 v208, v200, v196
	v_cvt_pk_bf16_f32 v212, v201, v197
	v_cvt_pk_bf16_f32 v216, v202, v198
	v_cvt_pk_bf16_f32 v220, v203, v199
	ds_write_b128 v5, v[208:211]
	ds_write_b128 v5, v[212:215] offset:160
	ds_write_b128 v5, v[216:219] offset:320
	ds_write_b128 v5, v[220:223] offset:480
	s_waitcnt lgkmcnt(0)
	s_barrier
	s_mov_b32 s17, 31
.Lhg_ploop:
	s_waitcnt vmcnt(16)
	v_lshlrev_b32_e32 v76, 16, v42
	v_and_b32_e32 v77, 0xffff0000, v42
	v_lshlrev_b32_e32 v78, 16, v43
	v_and_b32_e32 v79, 0xffff0000, v43
	v_lshlrev_b32_e32 v80, 16, v44
	v_and_b32_e32 v81, 0xffff0000, v44
	v_lshlrev_b32_e32 v82, 16, v45
	v_and_b32_e32 v83, 0xffff0000, v45
	v_lshlrev_b32_e32 v84, 16, v46
	v_and_b32_e32 v85, 0xffff0000, v46
	v_lshlrev_b32_e32 v86, 16, v47
	v_and_b32_e32 v87, 0xffff0000, v47
	v_lshlrev_b32_e32 v88, 16, v48
	v_and_b32_e32 v89, 0xffff0000, v48
	v_lshlrev_b32_e32 v90, 16, v49
	v_and_b32_e32 v91, 0xffff0000, v49
	v_lshlrev_b32_e32 v92, 16, v50
	v_and_b32_e32 v93, 0xffff0000, v50
	v_lshlrev_b32_e32 v94, 16, v51
	v_and_b32_e32 v95, 0xffff0000, v51
	v_lshlrev_b32_e32 v96, 16, v52
	v_and_b32_e32 v97, 0xffff0000, v52
	v_lshlrev_b32_e32 v98, 16, v53
	v_and_b32_e32 v99, 0xffff0000, v53
	v_lshlrev_b32_e32 v100, 16, v54
	v_and_b32_e32 v101, 0xffff0000, v54
	v_lshlrev_b32_e32 v102, 16, v55
	v_and_b32_e32 v103, 0xffff0000, v55
	v_lshlrev_b32_e32 v104, 16, v56
	v_and_b32_e32 v105, 0xffff0000, v56
	v_lshlrev_b32_e32 v106, 16, v57
	v_and_b32_e32 v107, 0xffff0000, v57
	v_lshlrev_b32_e32 v108, 16, v58
	v_and_b32_e32 v109, 0xffff0000, v58
	v_lshlrev_b32_e32 v110, 16, v59
	v_and_b32_e32 v111, 0xffff0000, v59
	v_lshlrev_b32_e32 v112, 16, v60
	v_and_b32_e32 v113, 0xffff0000, v60
	v_lshlrev_b32_e32 v114, 16, v61
	v_and_b32_e32 v115, 0xffff0000, v61
	v_lshlrev_b32_e32 v116, 16, v62
	v_and_b32_e32 v117, 0xffff0000, v62
	v_lshlrev_b32_e32 v118, 16, v63
	v_and_b32_e32 v119, 0xffff0000, v63
	v_lshlrev_b32_e32 v120, 16, v64
	v_and_b32_e32 v121, 0xffff0000, v64
	v_lshlrev_b32_e32 v122, 16, v65
	v_and_b32_e32 v123, 0xffff0000, v65
	v_lshlrev_b32_e32 v124, 16, v66
	v_and_b32_e32 v125, 0xffff0000, v66
	v_lshlrev_b32_e32 v126, 16, v67
	v_and_b32_e32 v127, 0xffff0000, v67
	v_lshlrev_b32_e32 v128, 16, v68
	v_and_b32_e32 v129, 0xffff0000, v68
	v_lshlrev_b32_e32 v130, 16, v69
	v_and_b32_e32 v131, 0xffff0000, v69
	v_lshlrev_b32_e32 v132, 16, v70
	v_and_b32_e32 v133, 0xffff0000, v70
	v_lshlrev_b32_e32 v134, 16, v71
	v_and_b32_e32 v135, 0xffff0000, v71
	v_lshlrev_b32_e32 v136, 16, v72
	v_and_b32_e32 v137, 0xffff0000, v72
	v_lshlrev_b32_e32 v138, 16, v73
	v_and_b32_e32 v139, 0xffff0000, v73
	global_load_dwordx2 v[42:43], v3, s[8:9]
	global_load_dwordx2 v[58:59], v2, s[8:9]
	s_add_u32 s8, s8, s10
	s_addc_u32 s9, s9, s11
	global_load_dwordx2 v[44:45], v3, s[8:9]
	global_load_dwordx2 v[60:61], v2, s[8:9]
	s_add_u32 s8, s8, s10
	s_addc_u32 s9, s9, s11
	global_load_dwordx2 v[46:47], v3, s[8:9]
	global_load_dwordx2 v[62:63], v2, s[8:9]
	s_add_u32 s8, s8, s10
	s_addc_u32 s9, s9, s11
	global_load_dwordx2 v[48:49], v3, s[8:9]
	global_load_dwordx2 v[64:65], v2, s[8:9]
	s_add_u32 s8, s8, s10
	s_addc_u32 s9, s9, s11
	global_load_dwordx2 v[50:51], v3, s[8:9]
	global_load_dwordx2 v[66:67], v2, s[8:9]
	s_add_u32 s8, s8, s10
	s_addc_u32 s9, s9, s11
	global_load_dwordx2 v[52:53], v3, s[8:9]
	global_load_dwordx2 v[68:69], v2, s[8:9]
	s_add_u32 s8, s8, s10
	s_addc_u32 s9, s9, s11
	global_load_dwordx2 v[54:55], v3, s[8:9]
	global_load_dwordx2 v[70:71], v2, s[8:9]
	s_add_u32 s8, s8, s10
	s_addc_u32 s9, s9, s11
	global_load_dwordx2 v[56:57], v3, s[8:9]
	global_load_dwordx2 v[72:73], v2, s[8:9]
	s_add_u32 s8, s8, s10
	s_addc_u32 s9, s9, s11
	s_cmp_lt_u32 s16, 63
	s_cselect_b32 s34, s12, s14
	s_cselect_b32 s35, s13, s15
	s_add_u32 s8, s8, s34
	s_addc_u32 s9, s9, s35
	s_add_i32 s16, s16, 1
	v_pk_add_f32 v[140:141], v[76:77], 1.0 op_sel_hi:[1,0] neg_lo:[1,0] neg_hi:[1,0]
	v_pk_add_f32 v[142:143], v[78:79], 1.0 op_sel_hi:[1,0] neg_lo:[1,0] neg_hi:[1,0]
	v_pk_add_f32 v[184:185], v[80:81], 1.0 op_sel_hi:[1,0] neg_lo:[1,0] neg_hi:[1,0]
	v_pk_add_f32 v[186:187], v[82:83], 1.0 op_sel_hi:[1,0] neg_lo:[1,0] neg_hi:[1,0]
	v_pk_mul_f32 v[144:145], v[140:141], v[184:185]
	v_pk_mul_f32 v[146:147], v[142:143], v[186:187]
	v_pk_add_f32 v[184:185], v[84:85], 1.0 op_sel_hi:[1,0] neg_lo:[1,0] neg_hi:[1,0]
	v_pk_add_f32 v[186:187], v[86:87], 1.0 op_sel_hi:[1,0] neg_lo:[1,0] neg_hi:[1,0]
	v_pk_mul_f32 v[148:149], v[144:145], v[184:185]
	v_pk_mul_f32 v[150:151], v[146:147], v[186:187]
	v_pk_add_f32 v[184:185], v[88:89], 1.0 op_sel_hi:[1,0] neg_lo:[1,0] neg_hi:[1,0]
	v_pk_add_f32 v[186:187], v[90:91], 1.0 op_sel_hi:[1,0] neg_lo:[1,0] neg_hi:[1,0]
	v_pk_mul_f32 v[152:153], v[148:149], v[184:185]
	v_pk_mul_f32 v[154:155], v[150:151], v[186:187]
	v_pk_add_f32 v[184:185], v[92:93], 1.0 op_sel_hi:[1,0] neg_lo:[1,0] neg_hi:[1,0]
	v_pk_add_f32 v[186:187], v[94:95], 1.0 op_sel_hi:[1,0] neg_lo:[1,0] neg_hi:[1,0]
	v_pk_mul_f32 v[156:157], v[152:153], v[184:185]
	v_pk_mul_f32 v[158:159], v[154:155], v[186:187]
	v_pk_add_f32 v[184:185], v[96:97], 1.0 op_sel_hi:[1,0] neg_lo:[1,0] neg_hi:[1,0]
	v_pk_add_f32 v[186:187], v[98:99], 1.0 op_sel_hi:[1,0] neg_lo:[1,0] neg_hi:[1,0]
	v_pk_mul_f32 v[160:161], v[156:157], v[184:185]
	v_pk_mul_f32 v[162:163], v[158:159], v[186:187]
	v_pk_add_f32 v[184:185], v[100:101], 1.0 op_sel_hi:[1,0] neg_lo:[1,0] neg_hi:[1,0]
	v_pk_add_f32 v[186:187], v[102:103], 1.0 op_sel_hi:[1,0] neg_lo:[1,0] neg_hi:[1,0]
	v_pk_mul_f32 v[164:165], v[160:161], v[184:185]
	v_pk_mul_f32 v[166:167], v[162:163], v[186:187]
	v_pk_add_f32 v[184:185], v[104:105], 1.0 op_sel_hi:[1,0] neg_lo:[1,0] neg_hi:[1,0]
	v_pk_add_f32 v[186:187], v[106:107], 1.0 op_sel_hi:[1,0] neg_lo:[1,0] neg_hi:[1,0]
	v_pk_mul_f32 v[168:169], v[164:165], v[184:185]
	v_pk_mul_f32 v[170:171], v[166:167], v[186:187]
	ds_write_b128 v6, v[168:171]
	ds_read_b128 v[192:195], v7
	ds_read_b128 v[196:199], v7 offset:128
	ds_read_b128 v[200:203], v7 offset:256
	ds_read_b128 v[204:207], v7 offset:384
	ds_read_b128 v[208:211], v7 offset:512
	ds_read_b128 v[212:215], v7 offset:640
	ds_read_b128 v[216:219], v7 offset:768
	s_waitcnt lgkmcnt(6)
	v_cndmask_b32_e64 v192, 1.0, v192, s[18:19]
	v_cndmask_b32_e64 v193, 1.0, v193, s[18:19]
	v_cndmask_b32_e64 v194, 1.0, v194, s[18:19]
	v_cndmask_b32_e64 v195, 1.0, v195, s[18:19]
	s_waitcnt lgkmcnt(5)
	v_cndmask_b32_e64 v196, 1.0, v196, s[20:21]
	v_cndmask_b32_e64 v197, 1.0, v197, s[20:21]
	v_cndmask_b32_e64 v198, 1.0, v198, s[20:21]
	v_cndmask_b32_e64 v199, 1.0, v199, s[20:21]
	s_waitcnt lgkmcnt(4)
	v_cndmask_b32_e64 v200, 1.0, v200, s[22:23]
	v_cndmask_b32_e64 v201, 1.0, v201, s[22:23]
	v_cndmask_b32_e64 v202, 1.0, v202, s[22:23]
	v_cndmask_b32_e64 v203, 1.0, v203, s[22:23]
	s_waitcnt lgkmcnt(3)
	v_cndmask_b32_e64 v204, 1.0, v204, s[24:25]
	v_cndmask_b32_e64 v205, 1.0, v205, s[24:25]
	v_cndmask_b32_e64 v206, 1.0, v206, s[24:25]
	v_cndmask_b32_e64 v207, 1.0, v207, s[24:25]
	s_waitcnt lgkmcnt(2)
	v_cndmask_b32_e64 v208, 1.0, v208, s[26:27]
	v_cndmask_b32_e64 v209, 1.0, v209, s[26:27]
	v_cndmask_b32_e64 v210, 1.0, v210, s[26:27]
	v_cndmask_b32_e64 v211, 1.0, v211, s[26:27]
	s_waitcnt lgkmcnt(1)
	v_cndmask_b32_e64 v212, 1.0, v212, s[28:29]
	v_cndmask_b32_e64 v213, 1.0, v213, s[28:29]
	v_cndmask_b32_e64 v214, 1.0, v214, s[28:29]
	v_cndmask_b32_e64 v215, 1.0, v215, s[28:29]
	s_waitcnt lgkmcnt(0)
	v_cndmask_b32_e64 v216, 1.0, v216, s[30:31]
	v_cndmask_b32_e64 v217, 1.0, v217, s[30:31]
	v_cndmask_b32_e64 v218, 1.0, v218, s[30:31]
	v_cndmask_b32_e64 v219, 1.0, v219, s[30:31]
	v_pk_mul_f32 v[192:193], v[192:193], v[196:197]
	v_pk_mul_f32 v[194:195], v[194:195], v[198:199]
	v_pk_mul_f32 v[200:201], v[200:201], v[204:205]
	v_pk_mul_f32 v[202:203], v[202:203], v[206:207]
	v_pk_mul_f32 v[208:209], v[208:209], v[212:213]
	v_pk_mul_f32 v[210:211], v[210:211], v[214:215]
	v_pk_mul_f32 v[192:193], v[192:193], v[200:201]
	v_pk_mul_f32 v[194:195], v[194:195], v[202:203]
	v_pk_mul_f32 v[208:209], v[208:209], v[216:217]
	v_pk_mul_f32 v[210:211], v[210:211], v[218:219]
	v_pk_mul_f32 v[176:177], v[192:193], v[208:209]
	v_pk_mul_f32 v[178:179], v[194:195], v[210:211]
	v_pk_mul_f32 v[188:189], v[176:177], v[168:169]
	v_pk_mul_f32 v[190:191], v[178:179], v[170:171]
	s_mov_b64 s[34:35], exec
	s_mov_b64 exec, s[30:31]
	ds_write_b128 v8, v[188:191] offset:512
	s_mov_b64 exec, s[34:35]
	v_max_f32_e32 v180, 0xda24260, v188
	v_max_f32_e32 v181, 0xda24260, v189
	v_max_f32_e32 v182, 0xda24260, v190
	v_max_f32_e32 v183, 0xda24260, v191
	v_rcp_f32_e32 v180, v180
	v_rcp_f32_e32 v181, v181
	v_rcp_f32_e32 v182, v182
	v_rcp_f32_e32 v183, v183
	v_pk_mul_f32 v[192:193], v[136:137], v[188:189]
	v_pk_mul_f32 v[194:195], v[138:139], v[190:191]
	v_pk_mul_f32 v[196:197], v[104:105], v[180:181]
	v_pk_mul_f32 v[198:199], v[106:107], v[182:183]
	v_cvt_pk_bf16_f32 v204, v192, v193
	v_cvt_pk_bf16_f32 v205, v194, v195
	ds_write_b64 v4, v[204:205] offset:20448
	v_cvt_pk_bf16_f32 v206, v196, v197
	v_cvt_pk_bf16_f32 v207, v198, v199
	ds_write_b64 v4, v[206:207] offset:57312
	v_pk_add_f32 v[184:185], v[104:105], 1.0 op_sel_hi:[1,0] neg_lo:[1,0] neg_hi:[1,0]
	v_pk_add_f32 v[186:187], v[106:107], 1.0 op_sel_hi:[1,0] neg_lo:[1,0] neg_hi:[1,0]
	v_pk_mul_f32 v[180:181], v[180:181], v[184:185]
	v_pk_mul_f32 v[182:183], v[182:183], v[186:187]
	v_pk_mul_f32 v[188:189], v[176:177], v[164:165]
	v_pk_mul_f32 v[190:191], v[178:179], v[166:167]
	v_pk_mul_f32 v[192:193], v[132:133], v[188:189]
	v_pk_mul_f32 v[194:195], v[134:135], v[190:191]
	v_pk_mul_f32 v[200:201], v[100:101], v[180:181]
	v_pk_mul_f32 v[202:203], v[102:103], v[182:183]
	v_cvt_pk_bf16_f32 v204, v192, v193
	v_cvt_pk_bf16_f32 v205, v194, v195
	ds_write_b64 v4, v[204:205] offset:20160
	v_cvt_pk_bf16_f32 v206, v200, v201
	v_cvt_pk_bf16_f32 v207, v202, v203
	ds_write_b64 v4, v[206:207] offset:57024
	v_cvt_pk_bf16_f32 v211, v200, v196
	v_cvt_pk_bf16_f32 v215, v201, v197
	v_cvt_pk_bf16_f32 v219, v202, v198
	v_cvt_pk_bf16_f32 v223, v203, v199
	v_pk_add_f32 v[184:185], v[100:101], 1.0 op_sel_hi:[1,0] neg_lo:[1,0] neg_hi:[1,0]
	v_pk_add_f32 v[186:187], v[102:103], 1.0 op_sel_hi:[1,0] neg_lo:[1,0] neg_hi:[1,0]
	v_pk_mul_f32 v[180:181], v[180:181], v[184:185]
	v_pk_mul_f32 v[182:183], v[182:183], v[186:187]
	v_pk_mul_f32 v[188:189], v[176:177], v[160:161]
	v_pk_mul_f32 v[190:191], v[178:179], v[162:163]
	v_pk_mul_f32 v[192:193], v[128:129], v[188:189]
	v_pk_mul_f32 v[194:195], v[130:131], v[190:191]
	v_pk_mul_f32 v[196:197], v[96:97], v[180:181]
	v_pk_mul_f32 v[198:199], v[98:99], v[182:183]
	v_cvt_pk_bf16_f32 v204, v192, v193
	v_cvt_pk_bf16_f32 v205, v194, v195
	ds_write_b64 v4, v[204:205] offset:19872
	v_cvt_pk_bf16_f32 v206, v196, v197
	v_cvt_pk_bf16_f32 v207, v198, v199
	ds_write_b64 v4, v[206:207] offset:56736
	v_pk_add_f32 v[184:185], v[96:97], 1.0 op_sel_hi:[1,0] neg_lo:[1,0] neg_hi:[1,0]
	v_pk_add_f32 v[186:187], v[98:99], 1.0 op_sel_hi:[1,0] neg_lo:[1,0] neg_hi:[1,0]
	v_pk_mul_f32 v[180:181], v[180:181], v[184:185]
	v_pk_mul_f32 v[182:183], v[182:183], v[186:187]
	v_pk_mul_f32 v[188:189], v[176:177], v[156:157]
	v_pk_mul_f32 v[190:191], v[178:179], v[158:159]
	v_pk_mul_f32 v[192:193], v[124:125], v[188:189]
	v_pk_mul_f32 v[194:195], v[126:127], v[190:191]
	v_pk_mul_f32 v[200:201], v[92:93], v[180:181]
	v_pk_mul_f32 v[202:203], v[94:95], v[182:183]
	v_cvt_pk_bf16_f32 v204, v192, v193
	v_cvt_pk_bf16_f32 v205, v194, v195
	ds_write_b64 v4, v[204:205] offset:19584
	v_cvt_pk_bf16_f32 v206, v200, v201
	v_cvt_pk_bf16_f32 v207, v202, v203
	ds_write_b64 v4, v[206:207] offset:56448
	v_cvt_pk_bf16_f32 v210, v200, v196
	v_cvt_pk_bf16_f32 v214, v201, v197
	v_cvt_pk_bf16_f32 v218, v202, v198
	v_cvt_pk_bf16_f32 v222, v203, v199
	v_pk_add_f32 v[184:185], v[92:93], 1.0 op_sel_hi:[1,0] neg_lo:[1,0] neg_hi:[1,0]
	v_pk_add_f32 v[186:187], v[94:95], 1.0 op_sel_hi:[1,0] neg_lo:[1,0] neg_hi:[1,0]
	v_pk_mul_f32 v[180:181], v[180:181], v[184:185]
	v_pk_mul_f32 v[182:183], v[182:183], v[186:187]
	v_pk_mul_f32 v[188:189], v[176:177], v[152:153]
	v_pk_mul_f32 v[190:191], v[178:179], v[154:155]
	v_pk_mul_f32 v[192:193], v[120:121], v[188:189]
	v_pk_mul_f32 v[194:195], v[122:123], v[190:191]
	v_pk_mul_f32 v[196:197], v[88:89], v[180:181]
	v_pk_mul_f32 v[198:199], v[90:91], v[182:183]
	v_cvt_pk_bf16_f32 v204, v192, v193
	v_cvt_pk_bf16_f32 v205, v194, v195
	ds_write_b64 v4, v[204:205] offset:19296
	v_cvt_pk_bf16_f32 v206, v196, v197
	v_cvt_pk_bf16_f32 v207, v198, v199
	ds_write_b64 v4, v[206:207] offset:56160
	v_pk_add_f32 v[184:185], v[88:89], 1.0 op_sel_hi:[1,0] neg_lo:[1,0] neg_hi:[1,0]
	v_pk_add_f32 v[186:187], v[90:91], 1.0 op_sel_hi:[1,0] neg_lo:[1,0] neg_hi:[1,0]
	v_pk_mul_f32 v[180:181], v[180:181], v[184:185]
	v_pk_mul_f32 v[182:183], v[182:183], v[186:187]
	v_pk_mul_f32 v[188:189], v[176:177], v[148:149]
	v_pk_mul_f32 v[190:191], v[178:179], v[150:151]
	v_pk_mul_f32 v[192:193], v[116:117], v[188:189]
	v_pk_mul_f32 v[194:195], v[118:119], v[190:191]
	v_pk_mul_f32 v[200:201], v[84:85], v[180:181]
	v_pk_mul_f32 v[202:203], v[86:87], v[182:183]
	v_cvt_pk_bf16_f32 v204, v192, v193
	v_cvt_pk_bf16_f32 v205, v194, v195
	ds_write_b64 v4, v[204:205] offset:19008
	v_cvt_pk_bf16_f32 v206, v200, v201
	v_cvt_pk_bf16_f32 v207, v202, v203
	ds_write_b64 v4, v[206:207] offset:55872
	v_cvt_pk_bf16_f32 v209, v200, v196
	v_cvt_pk_bf16_f32 v213, v201, v197
	v_cvt_pk_bf16_f32 v217, v202, v198
	v_cvt_pk_bf16_f32 v221, v203, v199
	v_pk_add_f32 v[184:185], v[84:85], 1.0 op_sel_hi:[1,0] neg_lo:[1,0] neg_hi:[1,0]
	v_pk_add_f32 v[186:187], v[86:87], 1.0 op_sel_hi:[1,0] neg_lo:[1,0] neg_hi:[1,0]
	v_pk_mul_f32 v[180:181], v[180:181], v[184:185]
	v_pk_mul_f32 v[182:183], v[182:183], v[186:187]
	v_pk_mul_f32 v[188:189], v[176:177], v[144:145]
	v_pk_mul_f32 v[190:191], v[178:179], v[146:147]
	v_pk_mul_f32 v[192:193], v[112:113], v[188:189]
	v_pk_mul_f32 v[194:195], v[114:115], v[190:191]
	v_pk_mul_f32 v[196:197], v[80:81], v[180:181]
	v_pk_mul_f32 v[198:199], v[82:83], v[182:183]
	v_cvt_pk_bf16_f32 v204, v192, v193
	v_cvt_pk_bf16_f32 v205, v194, v195
	ds_write_b64 v4, v[204:205] offset:18720
	v_cvt_pk_bf16_f32 v206, v196, v197
	v_cvt_pk_bf16_f32 v207, v198, v199
	ds_write_b64 v4, v[206:207] offset:55584
	v_pk_add_f32 v[184:185], v[80:81], 1.0 op_sel_hi:[1,0] neg_lo:[1,0] neg_hi:[1,0]
	v_pk_add_f32 v[186:187], v[82:83], 1.0 op_sel_hi:[1,0] neg_lo:[1,0] neg_hi:[1,0]
	v_pk_mul_f32 v[180:181], v[180:181], v[184:185]
	v_pk_mul_f32 v[182:183], v[182:183], v[186:187]
	v_pk_mul_f32 v[188:189], v[176:177], v[140:141]
	v_pk_mul_f32 v[190:191], v[178:179], v[142:143]
	v_pk_mul_f32 v[192:193], v[108:109], v[188:189]
	v_pk_mul_f32 v[194:195], v[110:111], v[190:191]
	v_pk_mul_f32 v[200:201], v[76:77], v[180:181]
	v_pk_mul_f32 v[202:203], v[78:79], v[182:183]
	v_cvt_pk_bf16_f32 v204, v192, v193
	v_cvt_pk_bf16_f32 v205, v194, v195
	ds_write_b64 v4, v[204:205] offset:18432
	v_cvt_pk_bf16_f32 v206, v200, v201
	v_cvt_pk_bf16_f32 v207, v202, v203
	ds_write_b64 v4, v[206:207] offset:55296
	v_cvt_pk_bf16_f32 v208, v200, v196
	v_cvt_pk_bf16_f32 v212, v201, v197
	v_cvt_pk_bf16_f32 v216, v202, v198
	v_cvt_pk_bf16_f32 v220, v203, v199
	ds_write_b128 v5, v[208:211] offset:20480
	ds_write_b128 v5, v[212:215] offset:20640
	ds_write_b128 v5, v[216:219] offset:20800
	ds_write_b128 v5, v[220:223] offset:20960
	s_waitcnt lgkmcnt(0)
	s_barrier
	s_cmp_eq_u32 s17, 0
	s_cbranch_scc1 .Lhg_pend
	s_waitcnt vmcnt(16)
	v_lshlrev_b32_e32 v76, 16, v10
	v_and_b32_e32 v77, 0xffff0000, v10
	v_lshlrev_b32_e32 v78, 16, v11
	v_and_b32_e32 v79, 0xffff0000, v11
	v_lshlrev_b32_e32 v80, 16, v12
	v_and_b32_e32 v81, 0xffff0000, v12
	v_lshlrev_b32_e32 v82, 16, v13
	v_and_b32_e32 v83, 0xffff0000, v13
	v_lshlrev_b32_e32 v84, 16, v14
	v_and_b32_e32 v85, 0xffff0000, v14
	v_lshlrev_b32_e32 v86, 16, v15
	v_and_b32_e32 v87, 0xffff0000, v15
	v_lshlrev_b32_e32 v88, 16, v16
	v_and_b32_e32 v89, 0xffff0000, v16
	v_lshlrev_b32_e32 v90, 16, v17
	v_and_b32_e32 v91, 0xffff0000, v17
	v_lshlrev_b32_e32 v92, 16, v18
	v_and_b32_e32 v93, 0xffff0000, v18
	v_lshlrev_b32_e32 v94, 16, v19
	v_and_b32_e32 v95, 0xffff0000, v19
	v_lshlrev_b32_e32 v96, 16, v20
	v_and_b32_e32 v97, 0xffff0000, v20
	v_lshlrev_b32_e32 v98, 16, v21
	v_and_b32_e32 v99, 0xffff0000, v21
	v_lshlrev_b32_e32 v100, 16, v22
	v_and_b32_e32 v101, 0xffff0000, v22
	v_lshlrev_b32_e32 v102, 16, v23
	v_and_b32_e32 v103, 0xffff0000, v23
	v_lshlrev_b32_e32 v104, 16, v24
	v_and_b32_e32 v105, 0xffff0000, v24
	v_lshlrev_b32_e32 v106, 16, v25
	v_and_b32_e32 v107, 0xffff0000, v25
	v_lshlrev_b32_e32 v108, 16, v26
	v_and_b32_e32 v109, 0xffff0000, v26
	v_lshlrev_b32_e32 v110, 16, v27
	v_and_b32_e32 v111, 0xffff0000, v27
	v_lshlrev_b32_e32 v112, 16, v28
	v_and_b32_e32 v113, 0xffff0000, v28
	v_lshlrev_b32_e32 v114, 16, v29
	v_and_b32_e32 v115, 0xffff0000, v29
	v_lshlrev_b32_e32 v116, 16, v30
	v_and_b32_e32 v117, 0xffff0000, v30
	v_lshlrev_b32_e32 v118, 16, v31
	v_and_b32_e32 v119, 0xffff0000, v31
	v_lshlrev_b32_e32 v120, 16, v32
	v_and_b32_e32 v121, 0xffff0000, v32
	v_lshlrev_b32_e32 v122, 16, v33
	v_and_b32_e32 v123, 0xffff0000, v33
	v_lshlrev_b32_e32 v124, 16, v34
	v_and_b32_e32 v125, 0xffff0000, v34
	v_lshlrev_b32_e32 v126, 16, v35
	v_and_b32_e32 v127, 0xffff0000, v35
	v_lshlrev_b32_e32 v128, 16, v36
	v_and_b32_e32 v129, 0xffff0000, v36
	v_lshlrev_b32_e32 v130, 16, v37
	v_and_b32_e32 v131, 0xffff0000, v37
	v_lshlrev_b32_e32 v132, 16, v38
	v_and_b32_e32 v133, 0xffff0000, v38
	v_lshlrev_b32_e32 v134, 16, v39
	v_and_b32_e32 v135, 0xffff0000, v39
	v_lshlrev_b32_e32 v136, 16, v40
	v_and_b32_e32 v137, 0xffff0000, v40
	v_lshlrev_b32_e32 v138, 16, v41
	v_and_b32_e32 v139, 0xffff0000, v41
	global_load_dwordx2 v[10:11], v3, s[8:9]
	global_load_dwordx2 v[26:27], v2, s[8:9]
	s_add_u32 s8, s8, s10
	s_addc_u32 s9, s9, s11
	global_load_dwordx2 v[12:13], v3, s[8:9]
	global_load_dwordx2 v[28:29], v2, s[8:9]
	s_add_u32 s8, s8, s10
	s_addc_u32 s9, s9, s11
	global_load_dwordx2 v[14:15], v3, s[8:9]
	global_load_dwordx2 v[30:31], v2, s[8:9]
	s_add_u32 s8, s8, s10
	s_addc_u32 s9, s9, s11
	global_load_dwordx2 v[16:17], v3, s[8:9]
	global_load_dwordx2 v[32:33], v2, s[8:9]
	s_add_u32 s8, s8, s10
	s_addc_u32 s9, s9, s11
	global_load_dwordx2 v[18:19], v3, s[8:9]
	global_load_dwordx2 v[34:35], v2, s[8:9]
	s_add_u32 s8, s8, s10
	s_addc_u32 s9, s9, s11
	global_load_dwordx2 v[20:21], v3, s[8:9]
	global_load_dwordx2 v[36:37], v2, s[8:9]
	s_add_u32 s8, s8, s10
	s_addc_u32 s9, s9, s11
	global_load_dwordx2 v[22:23], v3, s[8:9]
	global_load_dwordx2 v[38:39], v2, s[8:9]
	s_add_u32 s8, s8, s10
	s_addc_u32 s9, s9, s11
	global_load_dwordx2 v[24:25], v3, s[8:9]
	global_load_dwordx2 v[40:41], v2, s[8:9]
	s_add_u32 s8, s8, s10
	s_addc_u32 s9, s9, s11
	s_cmp_lt_u32 s16, 63
	s_cselect_b32 s34, s12, s14
	s_cselect_b32 s35, s13, s15
	s_add_u32 s8, s8, s34
	s_addc_u32 s9, s9, s35
	s_add_i32 s16, s16, 1
	v_pk_add_f32 v[140:141], v[76:77], 1.0 op_sel_hi:[1,0] neg_lo:[1,0] neg_hi:[1,0]
	v_pk_add_f32 v[142:143], v[78:79], 1.0 op_sel_hi:[1,0] neg_lo:[1,0] neg_hi:[1,0]
	v_pk_add_f32 v[184:185], v[80:81], 1.0 op_sel_hi:[1,0] neg_lo:[1,0] neg_hi:[1,0]
	v_pk_add_f32 v[186:187], v[82:83], 1.0 op_sel_hi:[1,0] neg_lo:[1,0] neg_hi:[1,0]
	v_pk_mul_f32 v[144:145], v[140:141], v[184:185]
	v_pk_mul_f32 v[146:147], v[142:143], v[186:187]
	v_pk_add_f32 v[184:185], v[84:85], 1.0 op_sel_hi:[1,0] neg_lo:[1,0] neg_hi:[1,0]
	v_pk_add_f32 v[186:187], v[86:87], 1.0 op_sel_hi:[1,0] neg_lo:[1,0] neg_hi:[1,0]
	v_pk_mul_f32 v[148:149], v[144:145], v[184:185]
	v_pk_mul_f32 v[150:151], v[146:147], v[186:187]
	v_pk_add_f32 v[184:185], v[88:89], 1.0 op_sel_hi:[1,0] neg_lo:[1,0] neg_hi:[1,0]
	v_pk_add_f32 v[186:187], v[90:91], 1.0 op_sel_hi:[1,0] neg_lo:[1,0] neg_hi:[1,0]
	v_pk_mul_f32 v[152:153], v[148:149], v[184:185]
	v_pk_mul_f32 v[154:155], v[150:151], v[186:187]
	v_pk_add_f32 v[184:185], v[92:93], 1.0 op_sel_hi:[1,0] neg_lo:[1,0] neg_hi:[1,0]
	v_pk_add_f32 v[186:187], v[94:95], 1.0 op_sel_hi:[1,0] neg_lo:[1,0] neg_hi:[1,0]
	v_pk_mul_f32 v[156:157], v[152:153], v[184:185]
	v_pk_mul_f32 v[158:159], v[154:155], v[186:187]
	v_pk_add_f32 v[184:185], v[96:97], 1.0 op_sel_hi:[1,0] neg_lo:[1,0] neg_hi:[1,0]
	v_pk_add_f32 v[186:187], v[98:99], 1.0 op_sel_hi:[1,0] neg_lo:[1,0] neg_hi:[1,0]
	v_pk_mul_f32 v[160:161], v[156:157], v[184:185]
	v_pk_mul_f32 v[162:163], v[158:159], v[186:187]
	v_pk_add_f32 v[184:185], v[100:101], 1.0 op_sel_hi:[1,0] neg_lo:[1,0] neg_hi:[1,0]
	v_pk_add_f32 v[186:187], v[102:103], 1.0 op_sel_hi:[1,0] neg_lo:[1,0] neg_hi:[1,0]
	v_pk_mul_f32 v[164:165], v[160:161], v[184:185]
	v_pk_mul_f32 v[166:167], v[162:163], v[186:187]
	v_pk_add_f32 v[184:185], v[104:105], 1.0 op_sel_hi:[1,0] neg_lo:[1,0] neg_hi:[1,0]
	v_pk_add_f32 v[186:187], v[106:107], 1.0 op_sel_hi:[1,0] neg_lo:[1,0] neg_hi:[1,0]
	v_pk_mul_f32 v[168:169], v[164:165], v[184:185]
	v_pk_mul_f32 v[170:171], v[166:167], v[186:187]
	ds_write_b128 v6, v[168:171]
	ds_read_b128 v[192:195], v7
	ds_read_b128 v[196:199], v7 offset:128
	ds_read_b128 v[200:203], v7 offset:256
	ds_read_b128 v[204:207], v7 offset:384
	ds_read_b128 v[208:211], v7 offset:512
	ds_read_b128 v[212:215], v7 offset:640
	ds_read_b128 v[216:219], v7 offset:768
	s_waitcnt lgkmcnt(6)
	v_cndmask_b32_e64 v192, 1.0, v192, s[18:19]
	v_cndmask_b32_e64 v193, 1.0, v193, s[18:19]
	v_cndmask_b32_e64 v194, 1.0, v194, s[18:19]
	v_cndmask_b32_e64 v195, 1.0, v195, s[18:19]
	s_waitcnt lgkmcnt(5)
	v_cndmask_b32_e64 v196, 1.0, v196, s[20:21]
	v_cndmask_b32_e64 v197, 1.0, v197, s[20:21]
	v_cndmask_b32_e64 v198, 1.0, v198, s[20:21]
	v_cndmask_b32_e64 v199, 1.0, v199, s[20:21]
	s_waitcnt lgkmcnt(4)
	v_cndmask_b32_e64 v200, 1.0, v200, s[22:23]
	v_cndmask_b32_e64 v201, 1.0, v201, s[22:23]
	v_cndmask_b32_e64 v202, 1.0, v202, s[22:23]
	v_cndmask_b32_e64 v203, 1.0, v203, s[22:23]
	s_waitcnt lgkmcnt(3)
	v_cndmask_b32_e64 v204, 1.0, v204, s[24:25]
	v_cndmask_b32_e64 v205, 1.0, v205, s[24:25]
	v_cndmask_b32_e64 v206, 1.0, v206, s[24:25]
	v_cndmask_b32_e64 v207, 1.0, v207, s[24:25]
	s_waitcnt lgkmcnt(2)
	v_cndmask_b32_e64 v208, 1.0, v208, s[26:27]
	v_cndmask_b32_e64 v209, 1.0, v209, s[26:27]
	v_cndmask_b32_e64 v210, 1.0, v210, s[26:27]
	v_cndmask_b32_e64 v211, 1.0, v211, s[26:27]
	s_waitcnt lgkmcnt(1)
	v_cndmask_b32_e64 v212, 1.0, v212, s[28:29]
	v_cndmask_b32_e64 v213, 1.0, v213, s[28:29]
	v_cndmask_b32_e64 v214, 1.0, v214, s[28:29]
	v_cndmask_b32_e64 v215, 1.0, v215, s[28:29]
	s_waitcnt lgkmcnt(0)
	v_cndmask_b32_e64 v216, 1.0, v216, s[30:31]
	v_cndmask_b32_e64 v217, 1.0, v217, s[30:31]
	v_cndmask_b32_e64 v218, 1.0, v218, s[30:31]
	v_cndmask_b32_e64 v219, 1.0, v219, s[30:31]
	v_pk_mul_f32 v[192:193], v[192:193], v[196:197]
	v_pk_mul_f32 v[194:195], v[194:195], v[198:199]
	v_pk_mul_f32 v[200:201], v[200:201], v[204:205]
	v_pk_mul_f32 v[202:203], v[202:203], v[206:207]
	v_pk_mul_f32 v[208:209], v[208:209], v[212:213]
	v_pk_mul_f32 v[210:211], v[210:211], v[214:215]
	v_pk_mul_f32 v[192:193], v[192:193], v[200:201]
	v_pk_mul_f32 v[194:195], v[194:195], v[202:203]
	v_pk_mul_f32 v[208:209], v[208:209], v[216:217]
	v_pk_mul_f32 v[210:211], v[210:211], v[218:219]
	v_pk_mul_f32 v[176:177], v[192:193], v[208:209]
	v_pk_mul_f32 v[178:179], v[194:195], v[210:211]
	v_pk_mul_f32 v[188:189], v[176:177], v[168:169]
	v_pk_mul_f32 v[190:191], v[178:179], v[170:171]
	s_mov_b64 s[34:35], exec
	s_mov_b64 exec, s[30:31]
	ds_write_b128 v8, v[188:191]
	s_mov_b64 exec, s[34:35]
	v_max_f32_e32 v180, 0xda24260, v188
	v_max_f32_e32 v181, 0xda24260, v189
	v_max_f32_e32 v182, 0xda24260, v190
	v_max_f32_e32 v183, 0xda24260, v191
	v_rcp_f32_e32 v180, v180
	v_rcp_f32_e32 v181, v181
	v_rcp_f32_e32 v182, v182
	v_rcp_f32_e32 v183, v183
	v_pk_mul_f32 v[192:193], v[136:137], v[188:189]
	v_pk_mul_f32 v[194:195], v[138:139], v[190:191]
	v_pk_mul_f32 v[196:197], v[104:105], v[180:181]
	v_pk_mul_f32 v[198:199], v[106:107], v[182:183]
	v_cvt_pk_bf16_f32 v204, v192, v193
	v_cvt_pk_bf16_f32 v205, v194, v195
	ds_write_b64 v4, v[204:205] offset:2016
	v_cvt_pk_bf16_f32 v206, v196, v197
	v_cvt_pk_bf16_f32 v207, v198, v199
	ds_write_b64 v4, v[206:207] offset:38880
	v_pk_add_f32 v[184:185], v[104:105], 1.0 op_sel_hi:[1,0] neg_lo:[1,0] neg_hi:[1,0]
	v_pk_add_f32 v[186:187], v[106:107], 1.0 op_sel_hi:[1,0] neg_lo:[1,0] neg_hi:[1,0]
	v_pk_mul_f32 v[180:181], v[180:181], v[184:185]
	v_pk_mul_f32 v[182:183], v[182:183], v[186:187]
	v_pk_mul_f32 v[188:189], v[176:177], v[164:165]
	v_pk_mul_f32 v[190:191], v[178:179], v[166:167]
	v_pk_mul_f32 v[192:193], v[132:133], v[188:189]
	v_pk_mul_f32 v[194:195], v[134:135], v[190:191]
	v_pk_mul_f32 v[200:201], v[100:101], v[180:181]
	v_pk_mul_f32 v[202:203], v[102:103], v[182:183]
	v_cvt_pk_bf16_f32 v204, v192, v193
	v_cvt_pk_bf16_f32 v205, v194, v195
	ds_write_b64 v4, v[204:205] offset:1728
	v_cvt_pk_bf16_f32 v206, v200, v201
	v_cvt_pk_bf16_f32 v207, v202, v203
	ds_write_b64 v4, v[206:207] offset:38592
	v_cvt_pk_bf16_f32 v211, v200, v196
	v_cvt_pk_bf16_f32 v215, v201, v197
	v_cvt_pk_bf16_f32 v219, v202, v198
	v_cvt_pk_bf16_f32 v223, v203, v199
	v_pk_add_f32 v[184:185], v[100:101], 1.0 op_sel_hi:[1,0] neg_lo:[1,0] neg_hi:[1,0]
	v_pk_add_f32 v[186:187], v[102:103], 1.0 op_sel_hi:[1,0] neg_lo:[1,0] neg_hi:[1,0]
	v_pk_mul_f32 v[180:181], v[180:181], v[184:185]
	v_pk_mul_f32 v[182:183], v[182:183], v[186:187]
	v_pk_mul_f32 v[188:189], v[176:177], v[160:161]
	v_pk_mul_f32 v[190:191], v[178:179], v[162:163]
	v_pk_mul_f32 v[192:193], v[128:129], v[188:189]
	v_pk_mul_f32 v[194:195], v[130:131], v[190:191]
	v_pk_mul_f32 v[196:197], v[96:97], v[180:181]
	v_pk_mul_f32 v[198:199], v[98:99], v[182:183]
	v_cvt_pk_bf16_f32 v204, v192, v193
	v_cvt_pk_bf16_f32 v205, v194, v195
	ds_write_b64 v4, v[204:205] offset:1440
	v_cvt_pk_bf16_f32 v206, v196, v197
	v_cvt_pk_bf16_f32 v207, v198, v199
	ds_write_b64 v4, v[206:207] offset:38304
	v_pk_add_f32 v[184:185], v[96:97], 1.0 op_sel_hi:[1,0] neg_lo:[1,0] neg_hi:[1,0]
	v_pk_add_f32 v[186:187], v[98:99], 1.0 op_sel_hi:[1,0] neg_lo:[1,0] neg_hi:[1,0]
	v_pk_mul_f32 v[180:181], v[180:181], v[184:185]
	v_pk_mul_f32 v[182:183], v[182:183], v[186:187]
	v_pk_mul_f32 v[188:189], v[176:177], v[156:157]
	v_pk_mul_f32 v[190:191], v[178:179], v[158:159]
	v_pk_mul_f32 v[192:193], v[124:125], v[188:189]
	v_pk_mul_f32 v[194:195], v[126:127], v[190:191]
	v_pk_mul_f32 v[200:201], v[92:93], v[180:181]
	v_pk_mul_f32 v[202:203], v[94:95], v[182:183]
	v_cvt_pk_bf16_f32 v204, v192, v193
	v_cvt_pk_bf16_f32 v205, v194, v195
	ds_write_b64 v4, v[204:205] offset:1152
	v_cvt_pk_bf16_f32 v206, v200, v201
	v_cvt_pk_bf16_f32 v207, v202, v203
	ds_write_b64 v4, v[206:207] offset:38016
	v_cvt_pk_bf16_f32 v210, v200, v196
	v_cvt_pk_bf16_f32 v214, v201, v197
	v_cvt_pk_bf16_f32 v218, v202, v198
	v_cvt_pk_bf16_f32 v222, v203, v199
	v_pk_add_f32 v[184:185], v[92:93], 1.0 op_sel_hi:[1,0] neg_lo:[1,0] neg_hi:[1,0]
	v_pk_add_f32 v[186:187], v[94:95], 1.0 op_sel_hi:[1,0] neg_lo:[1,0] neg_hi:[1,0]
	v_pk_mul_f32 v[180:181], v[180:181], v[184:185]
	v_pk_mul_f32 v[182:183], v[182:183], v[186:187]
	v_pk_mul_f32 v[188:189], v[176:177], v[152:153]
	v_pk_mul_f32 v[190:191], v[178:179], v[154:155]
	v_pk_mul_f32 v[192:193], v[120:121], v[188:189]
	v_pk_mul_f32 v[194:195], v[122:123], v[190:191]
	v_pk_mul_f32 v[196:197], v[88:89], v[180:181]
	v_pk_mul_f32 v[198:199], v[90:91], v[182:183]
	v_cvt_pk_bf16_f32 v204, v192, v193
	v_cvt_pk_bf16_f32 v205, v194, v195
	ds_write_b64 v4, v[204:205] offset:864
	v_cvt_pk_bf16_f32 v206, v196, v197
	v_cvt_pk_bf16_f32 v207, v198, v199
	ds_write_b64 v4, v[206:207] offset:37728
	v_pk_add_f32 v[184:185], v[88:89], 1.0 op_sel_hi:[1,0] neg_lo:[1,0] neg_hi:[1,0]
	v_pk_add_f32 v[186:187], v[90:91], 1.0 op_sel_hi:[1,0] neg_lo:[1,0] neg_hi:[1,0]
	v_pk_mul_f32 v[180:181], v[180:181], v[184:185]
	v_pk_mul_f32 v[182:183], v[182:183], v[186:187]
	v_pk_mul_f32 v[188:189], v[176:177], v[148:149]
	v_pk_mul_f32 v[190:191], v[178:179], v[150:151]
	v_pk_mul_f32 v[192:193], v[116:117], v[188:189]
	v_pk_mul_f32 v[194:195], v[118:119], v[190:191]
	v_pk_mul_f32 v[200:201], v[84:85], v[180:181]
	v_pk_mul_f32 v[202:203], v[86:87], v[182:183]
	v_cvt_pk_bf16_f32 v204, v192, v193
	v_cvt_pk_bf16_f32 v205, v194, v195
	ds_write_b64 v4, v[204:205] offset:576
	v_cvt_pk_bf16_f32 v206, v200, v201
	v_cvt_pk_bf16_f32 v207, v202, v203
	ds_write_b64 v4, v[206:207] offset:37440
	v_cvt_pk_bf16_f32 v209, v200, v196
	v_cvt_pk_bf16_f32 v213, v201, v197
	v_cvt_pk_bf16_f32 v217, v202, v198
	v_cvt_pk_bf16_f32 v221, v203, v199
	v_pk_add_f32 v[184:185], v[84:85], 1.0 op_sel_hi:[1,0] neg_lo:[1,0] neg_hi:[1,0]
	v_pk_add_f32 v[186:187], v[86:87], 1.0 op_sel_hi:[1,0] neg_lo:[1,0] neg_hi:[1,0]
	v_pk_mul_f32 v[180:181], v[180:181], v[184:185]
	v_pk_mul_f32 v[182:183], v[182:183], v[186:187]
	v_pk_mul_f32 v[188:189], v[176:177], v[144:145]
	v_pk_mul_f32 v[190:191], v[178:179], v[146:147]
	v_pk_mul_f32 v[192:193], v[112:113], v[188:189]
	v_pk_mul_f32 v[194:195], v[114:115], v[190:191]
	v_pk_mul_f32 v[196:197], v[80:81], v[180:181]
	v_pk_mul_f32 v[198:199], v[82:83], v[182:183]
	v_cvt_pk_bf16_f32 v204, v192, v193
	v_cvt_pk_bf16_f32 v205, v194, v195
	ds_write_b64 v4, v[204:205] offset:288
	v_cvt_pk_bf16_f32 v206, v196, v197
	v_cvt_pk_bf16_f32 v207, v198, v199
	ds_write_b64 v4, v[206:207] offset:37152
	v_pk_add_f32 v[184:185], v[80:81], 1.0 op_sel_hi:[1,0] neg_lo:[1,0] neg_hi:[1,0]
	v_pk_add_f32 v[186:187], v[82:83], 1.0 op_sel_hi:[1,0] neg_lo:[1,0] neg_hi:[1,0]
	v_pk_mul_f32 v[180:181], v[180:181], v[184:185]
	v_pk_mul_f32 v[182:183], v[182:183], v[186:187]
	v_pk_mul_f32 v[188:189], v[176:177], v[140:141]
	v_pk_mul_f32 v[190:191], v[178:179], v[142:143]
	v_pk_mul_f32 v[192:193], v[108:109], v[188:189]
	v_pk_mul_f32 v[194:195], v[110:111], v[190:191]
	v_pk_mul_f32 v[200:201], v[76:77], v[180:181]
	v_pk_mul_f32 v[202:203], v[78:79], v[182:183]
	v_cvt_pk_bf16_f32 v204, v192, v193
	v_cvt_pk_bf16_f32 v205, v194, v195
	ds_write_b64 v4, v[204:205]
	v_cvt_pk_bf16_f32 v206, v200, v201
	v_cvt_pk_bf16_f32 v207, v202, v203
	ds_write_b64 v4, v[206:207] offset:36864
	v_cvt_pk_bf16_f32 v208, v200, v196
	v_cvt_pk_bf16_f32 v212, v201, v197
	v_cvt_pk_bf16_f32 v216, v202, v198
	v_cvt_pk_bf16_f32 v220, v203, v199
	ds_write_b128 v5, v[208:211]
	ds_write_b128 v5, v[212:215] offset:160
	ds_write_b128 v5, v[216:219] offset:320
	ds_write_b128 v5, v[220:223] offset:480
	s_waitcnt lgkmcnt(0)
	s_barrier
	s_add_i32 s17, s17, -1
	s_branch .Lhg_ploop
.Lhg_pend:
	s_barrier
	s_branch .Lhg_done
.Lhg_sinit:
	s_sub_i32 s7, s6, 4
	v_and_b32_e32 v20, 15, v1
	v_lshrrev_b32_e32 v21, 4, v1
	s_lshl_b32 s28, s7, 4
	v_add_u32_e32 v22, s28, v20
	v_mul_u32_u24_e32 v2, 0x120, v22
	v_lshl_add_u32 v2, v21, 4, v2
	v_mul_u32_u24_e32 v3, 0x120, v20
	v_lshl_add_u32 v3, v21, 4, v3
	v_add_u32_e32 v6, 0x1e800, v3
	v_add_u32_e32 v3, 0x9000, v3
	v_mul_u32_u24_e32 v23, 0xa0, v20
	v_lshl_add_u32 v4, v21, 3, v23
	v_add_u32_e32 v4, 0x1c000, v4
	v_lshl_add_u32 v5, v21, 4, v23
	v_add_u32_e32 v5, 0x1c000, v5
	v_mul_u32_u24_e32 v7, 0x120, v20
	v_lshl_add_u32 v7, v21, 3, v7
	s_lshl_b32 s29, s7, 6
	v_add_u32_e32 v7, s29, v7
	v_add_u32_e32 v7, 0x1e800, v7
	s_lshl_b32 s29, s7, 5
	v_add_u32_e32 v24, s29, v20
	v_bfe_u32 v25, v24, 2, 3
	v_xor_b32_e32 v25, v25, v21
	v_xor_b32_e32 v26, 4, v25
	v_mul_u32_u24_e32 v24, 0xa0, v24
	v_add_u32_e32 v24, 0x12000, v24
	v_lshl_add_u32 v8, v25, 4, v24
	v_lshl_add_u32 v9, v26, 4, v24
	s_lshl_b32 s29, s7, 5
	s_add_i32 s29, s29, 16
	v_add_u32_e32 v24, s29, v20
	v_bfe_u32 v25, v24, 2, 3
	v_xor_b32_e32 v25, v25, v21
	v_xor_b32_e32 v26, 4, v25
	v_mul_u32_u24_e32 v24, 0xa0, v24
	v_add_u32_e32 v24, 0x12000, v24
	v_lshl_add_u32 v10, v25, 4, v24
	v_lshl_add_u32 v11, v26, 4, v24
	s_lshl_b32 s29, s7, 7
	v_lshl_add_u32 v12, v21, 4, s29
	v_add_u32_e32 v12, 0x24000, v12
	v_sub_u32_e32 v24, 0xfff, v22
	s_mov_b64 vcc, s[36:37]
	v_cndmask_b32_e32 v24, v24, v22, vcc
	s_lshl_b32 s29, s5, 14
	s_lshl_b32 s30, s4, 12
	s_add_i32 s29, s29, s30
	v_add_u32_e32 v24, s29, v24
	v_lshlrev_b32_e32 v24, 10, v24
	s_lshl_b32 s29, s3, 8
	s_lshl_b32 s30, s2, 6
	s_add_i32 s29, s29, s30
	v_lshl_add_u32 v25, v21, 3, s29
	v_add_u32_e32 v24, v24, v25
	v_mov_b32_e32 v25, 0
	v_readlane_b32 s30, v250, 12
	v_readlane_b32 s31, v250, 13
	v_lshl_add_u64 v[14:15], s[30:31], 0, v[24:25]
	s_lshl_b32 s29, s5, 1
	s_sub_i32 s29, 1, s29
	s_mul_i32 s26, s29, 0x10000
	s_ashr_i32 s27, s26, 31
	s_mul_i32 s10, s29, 0x98000
	s_ashr_i32 s11, s10, 31
	s_lshl_b32 s29, s7, 6
	v_add_u32_e32 v24, s29, v1
	v_lshrrev_b32_e32 v25, 2, v24
	v_and_b32_e32 v26, 3, v24
	v_mul_u32_u24_e32 v16, 0x2600, v25
	v_lshl_add_u32 v16, v26, 4, v16
	s_lshl_b32 s29, s4, 12
	s_mul_i32 s30, s5, 0xfc0
	s_add_i32 s29, s29, s30
	s_mul_i32 s29, s29, 0x2600
	s_lshl_b32 s30, s3, 8
	s_add_i32 s29, s29, s30
	s_lshl_b32 s30, s2, 6
	s_add_i32 s29, s29, s30
	s_add_i32 s29, s29, 0x101e00
	s_add_u32 s8, s98, s29
	s_addc_u32 s9, s99, 0
	s_mov_b32 s16, 0
	v_sub_u32_e32 v27, 63, v25
	s_mov_b64 vcc, s[36:37]
	v_cndmask_b32_e32 v27, v27, v25, vcc
	v_mul_u32_u24_e32 v17, 0x500, v26
	v_lshl_add_u32 v17, v27, 1, v17
	v_add_u32_e32 v17, 0x1c000, v17
	v_lshlrev_b32_e32 v24, 2, v21
	v_cmp_le_u32_e64 s[18:19], v24, v20
	v_add_u32_e32 v25, 1, v24
	v_cmp_le_u32_e64 s[20:21], v25, v20
	v_add_u32_e32 v25, 2, v24
	v_cmp_le_u32_e64 s[22:23], v25, v20
	v_add_u32_e32 v25, 3, v24
	v_cmp_le_u32_e64 s[24:25], v25, v20
	v_mov_b32_e32 v200, 0
	v_mov_b32_e32 v201, 0
	v_mov_b32_e32 v202, 0
	v_mov_b32_e32 v203, 0
	v_mov_b32_e32 v204, 0
	v_mov_b32_e32 v205, 0
	v_mov_b32_e32 v206, 0
	v_mov_b32_e32 v207, 0
	v_mov_b32_e32 v208, 0
	v_mov_b32_e32 v209, 0
	v_mov_b32_e32 v210, 0
	v_mov_b32_e32 v211, 0
	v_mov_b32_e32 v212, 0
	v_mov_b32_e32 v213, 0
	v_mov_b32_e32 v214, 0
	v_mov_b32_e32 v215, 0
	v_mov_b32_e32 v92, 0
	v_mov_b32_e32 v93, 0
	v_mov_b32_e32 v94, 0
	v_mov_b32_e32 v95, 0
	v_mov_b32_e32 v96, 0
	v_mov_b32_e32 v97, 0
	v_mov_b32_e32 v98, 0
	v_mov_b32_e32 v99, 0
	global_load_dwordx4 v[18:21], v16, s[8:9]
	s_cmp_lt_u32 s16, 63
	s_cselect_b32 s34, s10, 0
	s_cselect_b32 s35, s11, 0
	s_add_u32 s8, s8, s34
	s_addc_u32 s9, s9, s35
	s_add_i32 s16, s16, 1
	global_load_dwordx4 v[22:25], v16, s[8:9]
	s_cmp_lt_u32 s16, 63
	s_cselect_b32 s34, s10, 0
	s_cselect_b32 s35, s11, 0
	s_add_u32 s8, s8, s34
	s_addc_u32 s9, s9, s35
	s_add_i32 s16, s16, 1
	s_waitcnt vmcnt(0)
	s_waitcnt lgkmcnt(0)
	s_barrier
	s_mov_b64 s[38:39], exec
	v_readlane_b32 s40, v250, 10
	v_readlane_b32 s41, v250, 11
	s_and_b64 s[40:41], s[38:39], s[40:41]
	s_mov_b64 exec, s[40:41]
	s_cbranch_execz .Lhg_rel1
	s_mov_b64 s[40:41], exec
	v_mbcnt_lo_u32_b32 v224, s40, 0
	buffer_wbl2 sc1
	s_waitcnt vmcnt(0)
	v_mbcnt_hi_u32_b32 v224, s41, v224
	v_cmp_eq_u32_e32 vcc, 0, v224
	s_and_b64 s[42:43], exec, vcc
	s_mov_b64 exec, s[42:43]
	s_cbranch_execz .Lhg_rel1
	s_bcnt1_i32_b64 s42, s[40:41]
	s_lshl_b32 s40, s1, 7
	s_add_u32 s40, s98, s40
	s_addc_u32 s41, s99, 0
	v_mov_b32_e32 v224, 0x2000
	v_mov_b32_e32 v225, s42
	global_atomic_add v224, v225, s[40:41]
.Lhg_rel1:
	s_or_b64 exec, exec, s[38:39]
	s_waitcnt vmcnt(0)
	ds_write_b16 v17, v18
	ds_write_b16_d16_hi v17, v18 offset:160
	ds_write_b16 v17, v19 offset:320
	ds_write_b16_d16_hi v17, v19 offset:480
	ds_write_b16 v17, v20 offset:640
	ds_write_b16_d16_hi v17, v20 offset:800
	ds_write_b16 v17, v21 offset:960
	ds_write_b16_d16_hi v17, v21 offset:1120
	global_load_dwordx4 v[18:21], v16, s[8:9]
	s_cmp_lt_u32 s16, 63
	s_cselect_b32 s34, s10, 0
	s_cselect_b32 s35, s11, 0
	s_add_u32 s8, s8, s34
	s_addc_u32 s9, s9, s35
	s_add_i32 s16, s16, 1
	s_waitcnt lgkmcnt(0)
	s_barrier
	s_mov_b32 s17, 32
.Lhg_sloop:
	s_waitcnt vmcnt(3)
	ds_write_b16 v17, v22 offset:5120
	ds_write_b16_d16_hi v17, v22 offset:5280
	ds_write_b16 v17, v23 offset:5440
	ds_write_b16_d16_hi v17, v23 offset:5600
	ds_write_b16 v17, v24 offset:5760
	ds_write_b16_d16_hi v17, v24 offset:5920
	ds_write_b16 v17, v25 offset:6080
	ds_write_b16_d16_hi v17, v25 offset:6240
	ds_read_b128 v[28:31], v2
	ds_read_b128 v[32:35], v2 offset:64
	ds_read_b128 v[36:39], v2 offset:128
	ds_read_b128 v[40:43], v2 offset:192
	ds_read_b128 v[44:47], v3
	ds_read_b128 v[48:51], v3 offset:64
	ds_read_b128 v[52:55], v3 offset:128
	ds_read_b128 v[56:59], v3 offset:192
	s_waitcnt lgkmcnt(3)
	v_mfma_f32_16x16x32_bf16 v[76:79], v[44:47], v[28:31], 0
	s_waitcnt lgkmcnt(2)
	v_mfma_f32_16x16x32_bf16 v[76:79], v[48:51], v[32:35], v[76:79]
	s_waitcnt lgkmcnt(1)
	v_mfma_f32_16x16x32_bf16 v[76:79], v[52:55], v[36:39], v[76:79]
	s_waitcnt lgkmcnt(0)
	v_mfma_f32_16x16x32_bf16 v[76:79], v[56:59], v[40:43], v[76:79]
	s_cmp_lt_u32 s7, 1
	s_cbranch_scc1 .Lhg_sc0
	ds_read_b128 v[60:63], v3 offset:4608
	ds_read_b128 v[64:67], v3 offset:4672
	ds_read_b128 v[68:71], v3 offset:4736
	ds_read_b128 v[72:75], v3 offset:4800
	s_waitcnt lgkmcnt(3)
	v_mfma_f32_16x16x32_bf16 v[80:83], v[60:63], v[28:31], 0
	s_waitcnt lgkmcnt(2)
	v_mfma_f32_16x16x32_bf16 v[80:83], v[64:67], v[32:35], v[80:83]
	s_waitcnt lgkmcnt(1)
	v_mfma_f32_16x16x32_bf16 v[80:83], v[68:71], v[36:39], v[80:83]
	s_waitcnt lgkmcnt(0)
	v_mfma_f32_16x16x32_bf16 v[80:83], v[72:75], v[40:43], v[80:83]
	s_cmp_lt_u32 s7, 2
	s_cbranch_scc1 .Lhg_sc0
	ds_read_b128 v[44:47], v3 offset:9216
	ds_read_b128 v[48:51], v3 offset:9280
	ds_read_b128 v[52:55], v3 offset:9344
	ds_read_b128 v[56:59], v3 offset:9408
	s_waitcnt lgkmcnt(3)
	v_mfma_f32_16x16x32_bf16 v[84:87], v[44:47], v[28:31], 0
	s_waitcnt lgkmcnt(2)
	v_mfma_f32_16x16x32_bf16 v[84:87], v[48:51], v[32:35], v[84:87]
	s_waitcnt lgkmcnt(1)
	v_mfma_f32_16x16x32_bf16 v[84:87], v[52:55], v[36:39], v[84:87]
	s_waitcnt lgkmcnt(0)
	v_mfma_f32_16x16x32_bf16 v[84:87], v[56:59], v[40:43], v[84:87]
	s_cmp_lt_u32 s7, 3
	s_cbranch_scc1 .Lhg_sc0
	ds_read_b128 v[60:63], v3 offset:13824
	ds_read_b128 v[64:67], v3 offset:13888
	ds_read_b128 v[68:71], v3 offset:13952
	ds_read_b128 v[72:75], v3 offset:14016
	s_waitcnt lgkmcnt(3)
	v_mfma_f32_16x16x32_bf16 v[88:91], v[60:63], v[28:31], 0
	s_waitcnt lgkmcnt(2)
	v_mfma_f32_16x16x32_bf16 v[88:91], v[64:67], v[32:35], v[88:91]
	s_waitcnt lgkmcnt(1)
	v_mfma_f32_16x16x32_bf16 v[88:91], v[68:71], v[36:39], v[88:91]
	s_waitcnt lgkmcnt(0)
	v_mfma_f32_16x16x32_bf16 v[88:91], v[72:75], v[40:43], v[88:91]
.Lhg_sc0:
	ds_read_b64 v[100:101], v4
	ds_read_b64 v[102:103], v4 offset:32
	ds_read_b64 v[104:105], v4 offset:64
	ds_read_b64 v[106:107], v4 offset:96
	ds_read_b64 v[108:109], v4 offset:2560
	ds_read_b64 v[110:111], v4 offset:2592
	ds_read_b64 v[112:113], v4 offset:2624
	ds_read_b64 v[114:115], v4 offset:2656
	ds_read_b128 v[124:127], v6
	ds_read_b128 v[128:131], v6 offset:64
	ds_read_b128 v[132:135], v6 offset:128
	ds_read_b128 v[136:139], v6 offset:192
	ds_read_b128 v[140:143], v6 offset:4608
	ds_read_b128 v[144:147], v6 offset:4672
	ds_read_b128 v[148:151], v6 offset:4736
	ds_read_b128 v[152:155], v6 offset:4800
	s_nop 7
	s_cmp_lg_u32 s7, 0
	s_cbranch_scc1 .Lhg_nm0_0
	v_cndmask_b32_e64 v76, 0, v76, s[18:19]
	v_cndmask_b32_e64 v77, 0, v77, s[20:21]
	v_cndmask_b32_e64 v78, 0, v78, s[22:23]
	v_cndmask_b32_e64 v79, 0, v79, s[24:25]
.Lhg_nm0_0:
	v_cvt_pk_bf16_f32 v92, v76, v77
	v_cvt_pk_bf16_f32 v93, v78, v79
	s_cmp_lt_u32 s7, 1
	s_cbranch_scc1 .Lhg_pk0
	s_cmp_lg_u32 s7, 1
	s_cbranch_scc1 .Lhg_nm0_1
	v_cndmask_b32_e64 v80, 0, v80, s[18:19]
	v_cndmask_b32_e64 v81, 0, v81, s[20:21]
	v_cndmask_b32_e64 v82, 0, v82, s[22:23]
	v_cndmask_b32_e64 v83, 0, v83, s[24:25]
.Lhg_nm0_1:
	v_cvt_pk_bf16_f32 v94, v80, v81
	v_cvt_pk_bf16_f32 v95, v82, v83
	s_cmp_lt_u32 s7, 2
	s_cbranch_scc1 .Lhg_pk0
	s_cmp_lg_u32 s7, 2
	s_cbranch_scc1 .Lhg_nm0_2
	v_cndmask_b32_e64 v84, 0, v84, s[18:19]
	v_cndmask_b32_e64 v85, 0, v85, s[20:21]
	v_cndmask_b32_e64 v86, 0, v86, s[22:23]
	v_cndmask_b32_e64 v87, 0, v87, s[24:25]
.Lhg_nm0_2:
	v_cvt_pk_bf16_f32 v96, v84, v85
	v_cvt_pk_bf16_f32 v97, v86, v87
	s_cmp_lt_u32 s7, 3
	s_cbranch_scc1 .Lhg_pk0
	s_cmp_lg_u32 s7, 3
	s_cbranch_scc1 .Lhg_nm0_3
	v_cndmask_b32_e64 v88, 0, v88, s[18:19]
	v_cndmask_b32_e64 v89, 0, v89, s[20:21]
	v_cndmask_b32_e64 v90, 0, v90, s[22:23]
	v_cndmask_b32_e64 v91, 0, v91, s[24:25]
.Lhg_nm0_3:
	v_cvt_pk_bf16_f32 v98, v88, v89
	v_cvt_pk_bf16_f32 v99, v90, v91
.Lhg_pk0:
	ds_read_b128 v[156:159], v8
	ds_read_b128 v[160:163], v9
	ds_read_b128 v[164:167], v10
	ds_read_b128 v[168:171], v11
	ds_read_b128 v[176:179], v5
	ds_read_b128 v[180:183], v5 offset:64
	ds_read_b128 v[184:187], v5 offset:2560
	ds_read_b128 v[188:191], v5 offset:2624
	ds_read_b128 v[192:195], v12
	ds_read_b128 v[196:199], v12 offset:64
	s_waitcnt lgkmcnt(10)
	s_nop 0
	v_mfma_f32_16x16x32_bf16 v[116:119], v[100:103], v[92:95], 0
	v_mfma_f32_16x16x32_bf16 v[120:123], v[108:111], v[92:95], 0
	v_mfma_f32_16x16x32_bf16 v[116:119], v[104:107], v[96:99], v[116:119]
	v_mfma_f32_16x16x32_bf16 v[120:123], v[112:115], v[96:99], v[120:123]
	v_mfma_f32_16x16x32_bf16 v[116:119], v[124:127], v[28:31], v[116:119]
	v_mfma_f32_16x16x32_bf16 v[120:123], v[140:143], v[28:31], v[120:123]
	v_mfma_f32_16x16x32_bf16 v[116:119], v[128:131], v[32:35], v[116:119]
	v_mfma_f32_16x16x32_bf16 v[120:123], v[144:147], v[32:35], v[120:123]
	v_mfma_f32_16x16x32_bf16 v[116:119], v[132:135], v[36:39], v[116:119]
	v_mfma_f32_16x16x32_bf16 v[120:123], v[148:151], v[36:39], v[120:123]
	v_mfma_f32_16x16x32_bf16 v[116:119], v[136:139], v[40:43], v[116:119]
	v_mfma_f32_16x16x32_bf16 v[120:123], v[152:155], v[40:43], v[120:123]
	s_waitcnt lgkmcnt(0)
	v_mfma_f32_16x16x32_bf16 v[200:203], v[156:159], v[176:179], v[200:203]
	v_mfma_f32_16x16x32_bf16 v[204:207], v[156:159], v[184:187], v[204:207]
	v_mfma_f32_16x16x32_bf16 v[208:211], v[164:167], v[176:179], v[208:211]
	v_mfma_f32_16x16x32_bf16 v[212:215], v[164:167], v[184:187], v[212:215]
	v_mfma_f32_16x16x32_bf16 v[200:203], v[160:163], v[180:183], v[200:203]
	v_mfma_f32_16x16x32_bf16 v[204:207], v[160:163], v[188:191], v[204:207]
	v_mfma_f32_16x16x32_bf16 v[208:211], v[168:171], v[180:183], v[208:211]
	v_mfma_f32_16x16x32_bf16 v[212:215], v[168:171], v[188:191], v[212:215]
	v_cvt_pk_bf16_f32 v216, v116, v117
	v_cvt_pk_bf16_f32 v217, v118, v119
	v_cvt_pk_bf16_f32 v218, v120, v121
	v_cvt_pk_bf16_f32 v219, v122, v123
	global_store_dwordx2 v[14:15], v[216:217], off
	global_store_dwordx2 v[14:15], v[218:219], off offset:32
	v_lshl_add_u64 v[14:15], v[14:15], 0, s[26:27]
	global_load_dwordx4 v[22:25], v16, s[8:9]
	s_cmp_lt_u32 s16, 63
	s_cselect_b32 s34, s10, 0
	s_cselect_b32 s35, s11, 0
	s_add_u32 s8, s8, s34
	s_addc_u32 s9, s9, s35
	s_add_i32 s16, s16, 1
	s_nop 1
	v_pk_mul_f32 v[200:201], v[200:201], v[192:193]
	v_pk_mul_f32 v[202:203], v[202:203], v[194:195]
	v_pk_mul_f32 v[204:205], v[204:205], v[192:193]
	v_pk_mul_f32 v[206:207], v[206:207], v[194:195]
	v_pk_mul_f32 v[208:209], v[208:209], v[196:197]
	v_pk_mul_f32 v[210:211], v[210:211], v[198:199]
	v_pk_mul_f32 v[212:213], v[212:213], v[196:197]
	v_pk_mul_f32 v[214:215], v[214:215], v[198:199]
	v_cvt_pk_bf16_f32 v220, v200, v201
	v_cvt_pk_bf16_f32 v221, v202, v203
	ds_write_b64 v7, v[220:221] offset:9216
	v_cvt_pk_bf16_f32 v222, v204, v205
	v_cvt_pk_bf16_f32 v223, v206, v207
	ds_write_b64 v7, v[222:223] offset:13824
	v_cvt_pk_bf16_f32 v224, v208, v209
	v_cvt_pk_bf16_f32 v225, v210, v211
	ds_write_b64 v7, v[224:225] offset:9248
	v_cvt_pk_bf16_f32 v226, v212, v213
	v_cvt_pk_bf16_f32 v227, v214, v215
	ds_write_b64 v7, v[226:227] offset:13856
	s_waitcnt lgkmcnt(0)
	s_barrier
	s_waitcnt vmcnt(3)
	ds_write_b16 v17, v18
	ds_write_b16_d16_hi v17, v18 offset:160
	ds_write_b16 v17, v19 offset:320
	ds_write_b16_d16_hi v17, v19 offset:480
	ds_write_b16 v17, v20 offset:640
	ds_write_b16_d16_hi v17, v20 offset:800
	ds_write_b16 v17, v21 offset:960
	ds_write_b16_d16_hi v17, v21 offset:1120
	ds_read_b128 v[28:31], v2 offset:18432
	ds_read_b128 v[32:35], v2 offset:18496
	ds_read_b128 v[36:39], v2 offset:18560
	ds_read_b128 v[40:43], v2 offset:18624
	ds_read_b128 v[44:47], v3 offset:18432
	ds_read_b128 v[48:51], v3 offset:18496
	ds_read_b128 v[52:55], v3 offset:18560
	ds_read_b128 v[56:59], v3 offset:18624
	s_waitcnt lgkmcnt(3)
	v_mfma_f32_16x16x32_bf16 v[76:79], v[44:47], v[28:31], 0
	s_waitcnt lgkmcnt(2)
	v_mfma_f32_16x16x32_bf16 v[76:79], v[48:51], v[32:35], v[76:79]
	s_waitcnt lgkmcnt(1)
	v_mfma_f32_16x16x32_bf16 v[76:79], v[52:55], v[36:39], v[76:79]
	s_waitcnt lgkmcnt(0)
	v_mfma_f32_16x16x32_bf16 v[76:79], v[56:59], v[40:43], v[76:79]
	s_cmp_lt_u32 s7, 1
	s_cbranch_scc1 .Lhg_sc1
	ds_read_b128 v[60:63], v3 offset:23040
	ds_read_b128 v[64:67], v3 offset:23104
	ds_read_b128 v[68:71], v3 offset:23168
	ds_read_b128 v[72:75], v3 offset:23232
	s_waitcnt lgkmcnt(3)
	v_mfma_f32_16x16x32_bf16 v[80:83], v[60:63], v[28:31], 0
	s_waitcnt lgkmcnt(2)
	v_mfma_f32_16x16x32_bf16 v[80:83], v[64:67], v[32:35], v[80:83]
	s_waitcnt lgkmcnt(1)
	v_mfma_f32_16x16x32_bf16 v[80:83], v[68:71], v[36:39], v[80:83]
	s_waitcnt lgkmcnt(0)
	v_mfma_f32_16x16x32_bf16 v[80:83], v[72:75], v[40:43], v[80:83]
	s_cmp_lt_u32 s7, 2
	s_cbranch_scc1 .Lhg_sc1
	ds_read_b128 v[44:47], v3 offset:27648
	ds_read_b128 v[48:51], v3 offset:27712
	ds_read_b128 v[52:55], v3 offset:27776
	ds_read_b128 v[56:59], v3 offset:27840
	s_waitcnt lgkmcnt(3)
	v_mfma_f32_16x16x32_bf16 v[84:87], v[44:47], v[28:31], 0
	s_waitcnt lgkmcnt(2)
	v_mfma_f32_16x16x32_bf16 v[84:87], v[48:51], v[32:35], v[84:87]
	s_waitcnt lgkmcnt(1)
	v_mfma_f32_16x16x32_bf16 v[84:87], v[52:55], v[36:39], v[84:87]
	s_waitcnt lgkmcnt(0)
	v_mfma_f32_16x16x32_bf16 v[84:87], v[56:59], v[40:43], v[84:87]
	s_cmp_lt_u32 s7, 3
	s_cbranch_scc1 .Lhg_sc1
	ds_read_b128 v[60:63], v3 offset:32256
	ds_read_b128 v[64:67], v3 offset:32320
	ds_read_b128 v[68:71], v3 offset:32384
	ds_read_b128 v[72:75], v3 offset:32448
	s_waitcnt lgkmcnt(3)
	v_mfma_f32_16x16x32_bf16 v[88:91], v[60:63], v[28:31], 0
	s_waitcnt lgkmcnt(2)
	v_mfma_f32_16x16x32_bf16 v[88:91], v[64:67], v[32:35], v[88:91]
	s_waitcnt lgkmcnt(1)
	v_mfma_f32_16x16x32_bf16 v[88:91], v[68:71], v[36:39], v[88:91]
	s_waitcnt lgkmcnt(0)
	v_mfma_f32_16x16x32_bf16 v[88:91], v[72:75], v[40:43], v[88:91]
.Lhg_sc1:
	ds_read_b64 v[100:101], v4 offset:5120
	ds_read_b64 v[102:103], v4 offset:5152
	ds_read_b64 v[104:105], v4 offset:5184
	ds_read_b64 v[106:107], v4 offset:5216
	ds_read_b64 v[108:109], v4 offset:7680
	ds_read_b64 v[110:111], v4 offset:7712
	ds_read_b64 v[112:113], v4 offset:7744
	ds_read_b64 v[114:115], v4 offset:7776
	ds_read_b128 v[124:127], v6 offset:9216
	ds_read_b128 v[128:131], v6 offset:9280
	ds_read_b128 v[132:135], v6 offset:9344
	ds_read_b128 v[136:139], v6 offset:9408
	ds_read_b128 v[140:143], v6 offset:13824
	ds_read_b128 v[144:147], v6 offset:13888
	ds_read_b128 v[148:151], v6 offset:13952
	ds_read_b128 v[152:155], v6 offset:14016
	s_nop 7
	s_cmp_lg_u32 s7, 0
	s_cbranch_scc1 .Lhg_nm1_0
	v_cndmask_b32_e64 v76, 0, v76, s[18:19]
	v_cndmask_b32_e64 v77, 0, v77, s[20:21]
	v_cndmask_b32_e64 v78, 0, v78, s[22:23]
	v_cndmask_b32_e64 v79, 0, v79, s[24:25]

.Lhg_pk1:
	ds_read_b128 v[156:159], v8 offset:20480
	ds_read_b128 v[160:163], v9 offset:20480
	ds_read_b128 v[164:167], v10 offset:20480
	ds_read_b128 v[168:171], v11 offset:20480
	ds_read_b128 v[176:179], v5 offset:5120
	ds_read_b128 v[180:183], v5 offset:5184
	ds_read_b128 v[184:187], v5 offset:7680
	ds_read_b128 v[188:191], v5 offset:7744
	ds_read_b128 v[192:195], v12 offset:512
	ds_read_b128 v[196:199], v12 offset:576
	s_waitcnt lgkmcnt(10)
	s_nop 0
	v_mfma_f32_16x16x32_bf16 v[116:119], v[100:103], v[92:95], 0
	v_mfma_f32_16x16x32_bf16 v[120:123], v[108:111], v[92:95], 0
	v_mfma_f32_16x16x32_bf16 v[116:119], v[104:107], v[96:99], v[116:119]
	v_mfma_f32_16x16x32_bf16 v[120:123], v[112:115], v[96:99], v[120:123]
	v_mfma_f32_16x16x32_bf16 v[116:119], v[124:127], v[28:31], v[116:119]
	v_mfma_f32_16x16x32_bf16 v[120:123], v[140:143], v[28:31], v[120:123]
	v_mfma_f32_16x16x32_bf16 v[116:119], v[128:131], v[32:35], v[116:119]
	v_mfma_f32_16x16x32_bf16 v[120:123], v[144:147], v[32:35], v[120:123]
	v_mfma_f32_16x16x32_bf16 v[116:119], v[132:135], v[36:39], v[116:119]
	v_mfma_f32_16x16x32_bf16 v[120:123], v[148:151], v[36:39], v[120:123]
	v_mfma_f32_16x16x32_bf16 v[116:119], v[136:139], v[40:43], v[116:119]
	v_mfma_f32_16x16x32_bf16 v[120:123], v[152:155], v[40:43], v[120:123]
	s_waitcnt lgkmcnt(0)
	v_mfma_f32_16x16x32_bf16 v[200:203], v[156:159], v[176:179], v[200:203]
	v_mfma_f32_16x16x32_bf16 v[204:207], v[156:159], v[184:187], v[204:207]
	v_mfma_f32_16x16x32_bf16 v[208:211], v[164:167], v[176:179], v[208:211]
	v_mfma_f32_16x16x32_bf16 v[212:215], v[164:167], v[184:187], v[212:215]
	v_mfma_f32_16x16x32_bf16 v[200:203], v[160:163], v[180:183], v[200:203]
	v_mfma_f32_16x16x32_bf16 v[204:207], v[160:163], v[188:191], v[204:207]
	v_mfma_f32_16x16x32_bf16 v[208:211], v[168:171], v[180:183], v[208:211]
	v_mfma_f32_16x16x32_bf16 v[212:215], v[168:171], v[188:191], v[212:215]
	v_cvt_pk_bf16_f32 v216, v116, v117
	v_cvt_pk_bf16_f32 v217, v118, v119
	v_cvt_pk_bf16_f32 v218, v120, v121
	v_cvt_pk_bf16_f32 v219, v122, v123
	global_store_dwordx2 v[14:15], v[216:217], off
	global_store_dwordx2 v[14:15], v[218:219], off offset:32
	v_lshl_add_u64 v[14:15], v[14:15], 0, s[26:27]
	global_load_dwordx4 v[18:21], v16, s[8:9]
	s_cmp_lt_u32 s16, 63
	s_cselect_b32 s34, s10, 0
	s_cselect_b32 s35, s11, 0
	s_add_u32 s8, s8, s34
	s_addc_u32 s9, s9, s35
	s_add_i32 s16, s16, 1
	s_nop 1
	v_pk_mul_f32 v[200:201], v[200:201], v[192:193]
	v_pk_mul_f32 v[202:203], v[202:203], v[194:195]
	v_pk_mul_f32 v[204:205], v[204:205], v[192:193]
	v_pk_mul_f32 v[206:207], v[206:207], v[194:195]
	v_pk_mul_f32 v[208:209], v[208:209], v[196:197]
	v_pk_mul_f32 v[210:211], v[210:211], v[198:199]
	v_pk_mul_f32 v[212:213], v[212:213], v[196:197]
	v_pk_mul_f32 v[214:215], v[214:215], v[198:199]
	v_cvt_pk_bf16_f32 v220, v200, v201
	v_cvt_pk_bf16_f32 v221, v202, v203
	ds_write_b64 v7, v[220:221]
	v_cvt_pk_bf16_f32 v222, v204, v205
	v_cvt_pk_bf16_f32 v223, v206, v207
	ds_write_b64 v7, v[222:223] offset:4608
	v_cvt_pk_bf16_f32 v224, v208, v209
	v_cvt_pk_bf16_f32 v225, v210, v211
	ds_write_b64 v7, v[224:225] offset:32
	v_cvt_pk_bf16_f32 v226, v212, v213
	v_cvt_pk_bf16_f32 v227, v214, v215
	ds_write_b64 v7, v[226:227] offset:4640
	s_waitcnt lgkmcnt(0)
	s_barrier
	s_add_i32 s17, s17, -1
	s_cmp_lg_u32 s17, 0
	s_cbranch_scc1 .Lhg_sloop
.Lhg_done:
	s_waitcnt vmcnt(0) lgkmcnt(0)
.LBB0_438:
	s_mov_b64 s[0:1], 0
